# nt hint on Swiglu epilogue FF stores (both FFN-in copies)
# baseline (speedup 1.0000x reference)
.LBB0_635:
	v_mov_b32_e32 v128, v172
	v_mov_b32_e32 v129, v173
	s_lshl_b32 s0, s0, 8
	s_add_i32 s0, s0, s36
	v_lshlrev_b32_e32 v144, 3, v129
	v_add_u32_e32 v181, s0, v128
	v_ashrrev_i32_e32 v145, 31, v144
	v_lshlrev_b32_e32 v160, 5, v181
	v_lshl_add_u64 v[182:183], v[144:145], 2, s[76:77]
	v_lshl_add_u64 v[132:133], v[160:161], 2, v[182:183]
	v_add_u32_e32 v136, 0x200, v160
	v_mov_b32_e32 v137, v161
	global_load_dwordx4 v[128:131], v[132:133], off
	s_nop 0
	global_load_dwordx4 v[132:135], v[132:133], off offset:16
	v_lshl_add_u64 v[140:141], v[136:137], 2, v[182:183]
	global_load_dwordx4 v[136:139], v[140:141], off
	s_nop 0
	global_load_dwordx4 v[140:143], v[140:141], off offset:16
	v_and_b32_e32 v148, 64, v178
	s_lshl_b32 s0, s1, 7
	v_xor_b32_e32 v146, 16, v178
	v_add_u32_e32 v148, 64, v148
	s_or_b32 s0, s0, s37
	v_cmp_lt_i32_e32 vcc, v146, v148
	v_mov_b32_e32 v145, v161
	v_add_u32_e32 v170, s0, v144
	v_cndmask_b32_e32 v146, v178, v146, vcc
	v_add_u32_e32 v144, 0x400, v160
	v_mov_b32_e32 v147, v161
	v_mov_b32_e32 v187, v161
	v_lshlrev_b32_e32 v171, 2, v146
	v_add_u32_e32 v146, 0x600, v160
	v_add_u32_e32 v186, 0x1400, v160
	v_lshl_add_u64 v[144:145], v[144:145], 2, v[182:183]
	v_lshl_add_u64 v[146:147], v[146:147], 2, v[182:183]
	v_lshl_add_u64 v[212:213], v[186:187], 2, v[182:183]
	global_load_dwordx4 v[186:189], v[144:145], off
	global_load_dwordx4 v[190:193], v[144:145], off offset:16
	global_load_dwordx4 v[194:197], v[146:147], off
	global_load_dwordx4 v[198:201], v[146:147], off offset:16
	v_xor_b32_e32 v150, 32, v178
	v_cmp_lt_i32_e32 vcc, v150, v148
	v_mov_b32_e32 v149, v161
	v_mov_b32_e32 v151, v161
	v_cndmask_b32_e32 v148, v178, v150, vcc
	v_lshlrev_b32_e32 v214, 2, v148
	v_add_u32_e32 v148, 0x1000, v160
	v_add_u32_e32 v150, 0x1200, v160
	v_add_u32_e32 v160, 0x1600, v160
	v_lshl_add_u64 v[148:149], v[148:149], 2, v[182:183]
	v_lshl_add_u64 v[210:211], v[150:151], 2, v[182:183]
	v_pk_mul_f32 v[122:123], v[126:127], v[122:123]
	v_pk_mul_f32 v[120:121], v[124:125], v[120:121]
	v_pk_mul_f32 v[112:113], v[116:117], v[112:113]
	v_pk_mul_f32 v[114:115], v[118:119], v[114:115]
	v_pk_mul_f32 v[106:107], v[110:111], v[106:107]
	v_pk_mul_f32 v[104:105], v[108:109], v[104:105]
	v_pk_mul_f32 v[98:99], v[102:103], v[98:99]
	v_pk_mul_f32 v[96:97], v[100:101], v[96:97]
	v_pk_mul_f32 v[90:91], v[94:95], v[90:91]
	v_pk_mul_f32 v[88:89], v[92:93], v[88:89]
	v_pk_mul_f32 v[82:83], v[86:87], v[82:83]
	v_pk_mul_f32 v[80:81], v[84:85], v[80:81]
	v_pk_mul_f32 v[74:75], v[78:79], v[74:75]
	v_pk_mul_f32 v[72:73], v[76:77], v[72:73]
	v_pk_mul_f32 v[66:67], v[70:71], v[66:67]
	v_pk_mul_f32 v[64:65], v[68:69], v[64:65]
	v_pk_mul_f32 v[58:59], v[62:63], v[58:59]
	v_pk_mul_f32 v[56:57], v[60:61], v[56:57]
	v_pk_mul_f32 v[50:51], v[54:55], v[50:51]
	v_pk_mul_f32 v[48:49], v[52:53], v[48:49]
	v_pk_mul_f32 v[42:43], v[46:47], v[42:43]
	v_pk_mul_f32 v[40:41], v[44:45], v[40:41]
	v_pk_mul_f32 v[34:35], v[38:39], v[34:35]
	v_pk_mul_f32 v[32:33], v[36:37], v[32:33]
	v_pk_mul_f32 v[26:27], v[30:31], v[26:27]
	v_pk_mul_f32 v[24:25], v[28:29], v[24:25]
	v_pk_mul_f32 v[18:19], v[22:23], v[18:19]
	v_pk_mul_f32 v[16:17], v[20:21], v[16:17]
	v_pk_mul_f32 v[10:11], v[14:15], v[10:11]
	v_pk_mul_f32 v[8:9], v[12:13], v[8:9]
	v_pk_mul_f32 v[2:3], v[6:7], v[2:3]
	v_pk_mul_f32 v[0:1], v[4:5], v[0:1]
	s_waitcnt vmcnt(0)
	v_mov_b32_e32 v144, v128
	v_mov_b32_e32 v145, v132
	v_mov_b32_e32 v132, v129
	v_mov_b32_e32 v128, v130
	v_mov_b32_e32 v129, v134
	v_mov_b32_e32 v134, v131
	v_mov_b32_e32 v130, v136
	v_mov_b32_e32 v131, v140
	v_mov_b32_e32 v140, v137
	v_mov_b32_e32 v136, v138
	v_mov_b32_e32 v137, v142
	v_mov_b32_e32 v142, v139
	v_pk_add_f32 v[132:133], v[144:145], v[132:133]
	v_pk_add_f32 v[128:129], v[128:129], v[134:135]
	v_pk_add_f32 v[130:131], v[130:131], v[140:141]
	v_pk_add_f32 v[134:135], v[136:137], v[142:143]
	v_pk_add_f32 v[128:129], v[132:133], v[128:129]
	v_pk_add_f32 v[130:131], v[130:131], v[134:135]
	v_add_f32_e32 v128, v128, v129
	v_add_f32_e32 v129, v130, v131
	ds_bpermute_b32 v130, v171, v128
	ds_bpermute_b32 v131, v171, v129
	global_load_dwordx4 v[202:205], v[148:149], off
	global_load_dwordx4 v[206:209], v[148:149], off offset:16
	s_nop 0
	global_load_dwordx4 v[148:151], v[210:211], off
	global_load_dwordx4 v[144:147], v[210:211], off offset:16
	global_load_dwordx4 v[140:143], v[212:213], off
	global_load_dwordx4 v[136:139], v[212:213], off offset:16
	s_waitcnt lgkmcnt(1)
	v_add_f32_e32 v130, v128, v130
	ds_bpermute_b32 v132, v214, v130
	s_waitcnt lgkmcnt(1)
	v_add_f32_e32 v131, v129, v131
	v_lshl_add_u64 v[128:129], v[160:161], 2, v[182:183]
	ds_bpermute_b32 v133, v214, v131
	s_waitcnt lgkmcnt(1)
	v_add_f32_e32 v130, v130, v132
	v_fmamk_f32 v130, v130, 0x3a000000, v179
	v_mul_f32_e32 v132, 0x4f800000, v130
	v_cmp_gt_f32_e32 vcc, s44, v130
	s_waitcnt lgkmcnt(0)
	v_add_f32_e32 v131, v131, v133
	v_fmamk_f32 v131, v131, 0x3a000000, v179
	v_cndmask_b32_e32 v160, v130, v132, vcc
	v_sqrt_f32_e32 v183, v160
	v_mul_f32_e32 v133, 0x4f800000, v131
	v_cmp_gt_f32_e64 s[0:1], s44, v131
	v_add_u32_e32 v211, -1, v183
	v_add_u32_e32 v212, 1, v183
	v_fma_f32 v216, -v211, v183, v160
	v_fma_f32 v217, -v212, v183, v160
	v_cmp_ge_f32_e64 s[6:7], 0, v216
	v_cndmask_b32_e64 v182, v131, v133, s[0:1]
	v_sqrt_f32_e32 v210, v182
	v_cndmask_b32_e64 v183, v183, v211, s[6:7]
	v_cmp_lt_f32_e64 s[6:7], 0, v217
	global_load_dwordx4 v[132:135], v[128:129], off
	s_nop 0
	global_load_dwordx4 v[128:131], v[128:129], off offset:16
	v_cndmask_b32_e64 v183, v183, v212, s[6:7]
	v_mul_f32_e32 v211, 0x37800000, v183
	v_cndmask_b32_e32 v183, v183, v211, vcc
	v_cmp_class_f32_e32 vcc, v160, v180
	v_add_u32_e32 v213, -1, v210
	v_fma_f32 v218, -v213, v210, v182
	v_cndmask_b32_e32 v160, v183, v160, vcc
	v_div_scale_f32 v183, s[6:7], v160, v160, 1.0
	v_rcp_f32_e32 v211, v183
	v_add_u32_e32 v215, 1, v210
	v_cmp_ge_f32_e32 vcc, 0, v218
	v_fma_f32 v219, -v215, v210, v182
	v_cmp_lt_f32_e64 s[6:7], 0, v219
	v_cndmask_b32_e32 v210, v210, v213, vcc
	v_fma_f32 v213, -v183, v211, 1.0
	v_div_scale_f32 v212, vcc, 1.0, v160, 1.0
	v_fmac_f32_e32 v211, v213, v211
	v_mul_f32_e32 v213, v212, v211
	v_fma_f32 v216, -v183, v213, v212
	v_fmac_f32_e32 v213, v216, v211
	v_fma_f32 v212, -v183, v213, v212
	v_cndmask_b32_e64 v183, v210, v215, s[6:7]
	v_mul_f32_e32 v210, 0x37800000, v183
	v_cndmask_b32_e64 v183, v183, v210, s[0:1]
	v_cmp_class_f32_e64 s[0:1], v182, v180
	s_nop 1
	v_cndmask_b32_e64 v210, v183, v182, s[0:1]
	v_mov_b32_e32 v182, v186
	v_mov_b32_e32 v183, v190
	v_mov_b32_e32 v190, v187
	v_mov_b32_e32 v186, v188
	v_mov_b32_e32 v187, v192
	v_mov_b32_e32 v192, v189
	v_pk_add_f32 v[182:183], v[182:183], v[190:191]
	v_pk_add_f32 v[186:187], v[186:187], v[192:193]
	v_div_scale_f32 v215, s[0:1], v210, v210, 1.0
	v_pk_add_f32 v[182:183], v[182:183], v[186:187]
	v_rcp_f32_e32 v216, v215
	v_add_f32_e32 v182, v182, v183
	ds_bpermute_b32 v183, v171, v182
	v_div_fmas_f32 v186, v212, v211, v213
	v_div_fixup_f32 v160, v186, v160, 1.0
	v_fma_f32 v186, -v215, v216, 1.0
	v_fmac_f32_e32 v216, v186, v216
	s_waitcnt lgkmcnt(0)
	v_add_f32_e32 v182, v182, v183
	ds_bpermute_b32 v183, v214, v182
	v_div_scale_f32 v186, vcc, 1.0, v210, 1.0
	v_mul_f32_e32 v188, v186, v216
	v_fma_f32 v187, -v215, v188, v186
	s_waitcnt lgkmcnt(0)
	v_add_f32_e32 v182, v182, v183
	v_fmamk_f32 v182, v182, 0x3a000000, v179
	v_mul_f32_e32 v183, 0x4f800000, v182
	v_cmp_gt_f32_e64 s[0:1], s44, v182
	v_fmac_f32_e32 v188, v187, v216
	v_fma_f32 v189, -v215, v188, v186
	v_cndmask_b32_e64 v182, v182, v183, s[0:1]
	v_sqrt_f32_e32 v183, v182
	s_nop 0
	v_add_u32_e32 v186, -1, v183
	v_fma_f32 v187, -v186, v183, v182
	v_cmp_ge_f32_e64 s[6:7], 0, v187
	v_add_u32_e32 v187, 1, v183
	s_nop 0
	v_cndmask_b32_e64 v186, v183, v186, s[6:7]
	v_fma_f32 v183, -v187, v183, v182
	v_cmp_lt_f32_e64 s[6:7], 0, v183
	s_nop 1
	v_cndmask_b32_e64 v183, v186, v187, s[6:7]
	v_mul_f32_e32 v186, 0x37800000, v183
	v_cndmask_b32_e64 v183, v183, v186, s[0:1]
	v_cmp_class_f32_e64 s[0:1], v182, v180
	v_mov_b32_e32 v186, v196
	v_mov_b32_e32 v187, v200
	v_cndmask_b32_e64 v190, v183, v182, s[0:1]
	v_mov_b32_e32 v182, v194
	v_mov_b32_e32 v183, v198
	v_mov_b32_e32 v198, v195
	v_mov_b32_e32 v200, v197
	v_pk_add_f32 v[182:183], v[182:183], v[198:199]
	v_pk_add_f32 v[186:187], v[186:187], v[200:201]
	v_div_scale_f32 v191, s[0:1], v190, v190, 1.0
	v_pk_add_f32 v[182:183], v[182:183], v[186:187]
	v_rcp_f32_e32 v192, v191
	v_add_f32_e32 v182, v182, v183
	ds_bpermute_b32 v183, v171, v182
	v_div_fmas_f32 v186, v189, v216, v188
	v_div_fixup_f32 v188, v186, v210, 1.0
	v_fma_f32 v186, -v191, v192, 1.0
	v_fmac_f32_e32 v192, v186, v192
	s_waitcnt lgkmcnt(0)
	v_add_f32_e32 v182, v182, v183
	ds_bpermute_b32 v183, v214, v182
	v_div_scale_f32 v186, vcc, 1.0, v190, 1.0
	v_mul_f32_e32 v189, v186, v192
	v_fma_f32 v187, -v191, v189, v186
	s_waitcnt lgkmcnt(0)
	v_add_f32_e32 v182, v182, v183
	v_fmamk_f32 v182, v182, 0x3a000000, v179
	v_mul_f32_e32 v183, 0x4f800000, v182
	v_cmp_gt_f32_e64 s[0:1], s44, v182
	v_fmac_f32_e32 v189, v187, v192
	v_fma_f32 v191, -v191, v189, v186
	v_cndmask_b32_e64 v182, v182, v183, s[0:1]
	v_sqrt_f32_e32 v183, v182
	s_nop 0
	v_add_u32_e32 v186, -1, v183
	v_fma_f32 v187, -v186, v183, v182
	v_cmp_ge_f32_e64 s[6:7], 0, v187
	v_add_u32_e32 v187, 1, v183
	s_nop 0
	v_cndmask_b32_e64 v186, v183, v186, s[6:7]
	v_fma_f32 v183, -v187, v183, v182
	v_cmp_lt_f32_e64 s[6:7], 0, v183
	s_nop 1
	v_cndmask_b32_e64 v183, v186, v187, s[6:7]
	v_mul_f32_e32 v186, 0x37800000, v183
	v_cndmask_b32_e64 v183, v183, v186, s[0:1]
	v_cmp_class_f32_e64 s[0:1], v182, v180
	s_waitcnt vmcnt(7)
	v_mov_b32_e32 v186, v204
	s_waitcnt vmcnt(6)
	v_mov_b32_e32 v187, v208
	v_cndmask_b32_e64 v193, v183, v182, s[0:1]
	v_mov_b32_e32 v182, v202
	v_mov_b32_e32 v183, v206
	v_mov_b32_e32 v206, v203
	v_mov_b32_e32 v208, v205
	v_pk_add_f32 v[182:183], v[182:183], v[206:207]
	v_pk_add_f32 v[186:187], v[186:187], v[208:209]
	v_div_scale_f32 v194, s[0:1], v193, v193, 1.0
	v_pk_add_f32 v[182:183], v[182:183], v[186:187]
	v_rcp_f32_e32 v195, v194
	v_add_f32_e32 v182, v182, v183
	ds_bpermute_b32 v183, v171, v182
	v_div_fmas_f32 v186, v191, v192, v189
	v_fma_f32 v187, -v194, v195, 1.0
	v_fmac_f32_e32 v195, v187, v195
	v_div_scale_f32 v187, vcc, 1.0, v193, 1.0
	s_waitcnt lgkmcnt(0)
	v_add_f32_e32 v182, v182, v183
	ds_bpermute_b32 v183, v214, v182
	v_mul_f32_e32 v189, v187, v195
	v_div_fixup_f32 v186, v186, v190, 1.0
	v_fma_f32 v190, -v194, v189, v187
	v_fmac_f32_e32 v189, v190, v195
	s_waitcnt lgkmcnt(0)
	v_add_f32_e32 v182, v182, v183
	v_fmamk_f32 v182, v182, 0x3a000000, v179
	v_mul_f32_e32 v183, 0x4f800000, v182
	v_cmp_gt_f32_e64 s[0:1], s44, v182
	v_fma_f32 v187, -v194, v189, v187
	s_nop 0
	v_cndmask_b32_e64 v182, v182, v183, s[0:1]
	v_sqrt_f32_e32 v183, v182
	s_nop 0
	v_add_u32_e32 v190, -1, v183
	v_fma_f32 v191, -v190, v183, v182
	v_cmp_ge_f32_e64 s[6:7], 0, v191
	v_add_u32_e32 v191, 1, v183
	s_nop 0
	v_cndmask_b32_e64 v190, v183, v190, s[6:7]
	v_fma_f32 v183, -v191, v183, v182
	v_cmp_lt_f32_e64 s[6:7], 0, v183
	s_nop 1
	v_cndmask_b32_e64 v183, v190, v191, s[6:7]
	v_mul_f32_e32 v190, 0x37800000, v183
	v_cndmask_b32_e64 v183, v183, v190, s[0:1]
	v_cmp_class_f32_e64 s[0:1], v182, v180
	s_nop 1
	v_cndmask_b32_e64 v190, v183, v182, s[0:1]
	s_waitcnt vmcnt(5)
	v_mov_b32_e32 v182, v148
	s_waitcnt vmcnt(4)
	v_mov_b32_e32 v183, v144
	v_mov_b32_e32 v144, v149
	v_mov_b32_e32 v148, v150
	v_mov_b32_e32 v149, v146
	v_mov_b32_e32 v146, v151
	v_pk_add_f32 v[144:145], v[182:183], v[144:145]
	v_pk_add_f32 v[146:147], v[148:149], v[146:147]
	v_div_scale_f32 v191, s[0:1], v190, v190, 1.0
	v_pk_add_f32 v[144:145], v[144:145], v[146:147]
	v_rcp_f32_e32 v192, v191
	v_add_f32_e32 v144, v144, v145
	ds_bpermute_b32 v145, v171, v144
	v_div_fmas_f32 v146, v187, v195, v189
	v_fma_f32 v147, -v191, v192, 1.0
	v_fmac_f32_e32 v192, v147, v192
	v_div_scale_f32 v147, vcc, 1.0, v190, 1.0
	s_waitcnt lgkmcnt(0)
	v_add_f32_e32 v144, v144, v145
	ds_bpermute_b32 v145, v214, v144
	v_mul_f32_e32 v148, v147, v192
	v_fma_f32 v149, -v191, v148, v147
	v_fmac_f32_e32 v148, v149, v192
	v_fma_f32 v147, -v191, v148, v147
	s_waitcnt lgkmcnt(0)
	v_add_f32_e32 v144, v144, v145
	v_fmamk_f32 v144, v144, 0x3a000000, v179
	v_mul_f32_e32 v145, 0x4f800000, v144
	v_cmp_gt_f32_e64 s[0:1], s44, v144
	v_div_fixup_f32 v146, v146, v193, 1.0
	s_nop 0
	v_cndmask_b32_e64 v144, v144, v145, s[0:1]
	v_sqrt_f32_e32 v145, v144
	s_nop 0
	v_add_u32_e32 v149, -1, v145
	v_fma_f32 v150, -v149, v145, v144
	v_cmp_ge_f32_e64 s[6:7], 0, v150
	v_add_u32_e32 v150, 1, v145
	s_nop 0
	v_cndmask_b32_e64 v149, v145, v149, s[6:7]
	v_fma_f32 v145, -v150, v145, v144
	v_cmp_lt_f32_e64 s[6:7], 0, v145
	s_nop 1
	v_cndmask_b32_e64 v145, v149, v150, s[6:7]
	v_mul_f32_e32 v149, 0x37800000, v145
	v_cndmask_b32_e64 v145, v145, v149, s[0:1]
	v_cmp_class_f32_e64 s[0:1], v144, v180
	s_nop 1
	v_cndmask_b32_e64 v149, v145, v144, s[0:1]
	s_waitcnt vmcnt(3)
	v_mov_b32_e32 v144, v140
	s_waitcnt vmcnt(2)
	v_mov_b32_e32 v145, v136
	v_mov_b32_e32 v136, v141
	v_mov_b32_e32 v140, v142
	v_mov_b32_e32 v141, v138
	v_mov_b32_e32 v138, v143
	v_pk_add_f32 v[136:137], v[144:145], v[136:137]
	v_pk_add_f32 v[138:139], v[140:141], v[138:139]
	v_div_scale_f32 v150, s[0:1], v149, v149, 1.0
	v_pk_add_f32 v[136:137], v[136:137], v[138:139]
	v_rcp_f32_e32 v151, v150
	v_add_f32_e32 v136, v136, v137
	ds_bpermute_b32 v137, v171, v136
	v_div_fmas_f32 v138, v147, v192, v148
	v_fma_f32 v139, -v150, v151, 1.0
	v_fmac_f32_e32 v151, v139, v151
	v_div_scale_f32 v139, vcc, 1.0, v149, 1.0
	s_waitcnt lgkmcnt(0)
	v_add_f32_e32 v136, v136, v137
	ds_bpermute_b32 v137, v214, v136
	v_mul_f32_e32 v140, v139, v151
	v_fma_f32 v141, -v150, v140, v139
	v_fmac_f32_e32 v140, v141, v151
	v_fma_f32 v139, -v150, v140, v139
	s_waitcnt lgkmcnt(0)
	v_add_f32_e32 v136, v136, v137
	v_fmamk_f32 v136, v136, 0x3a000000, v179
	v_mul_f32_e32 v137, 0x4f800000, v136
	v_cmp_gt_f32_e64 s[0:1], s44, v136
	v_div_fixup_f32 v138, v138, v190, 1.0
	s_nop 0
	v_cndmask_b32_e64 v136, v136, v137, s[0:1]
	v_sqrt_f32_e32 v137, v136
	s_nop 0
	v_add_u32_e32 v141, -1, v137
	v_fma_f32 v142, -v141, v137, v136
	v_cmp_ge_f32_e64 s[6:7], 0, v142
	v_add_u32_e32 v142, 1, v137
	s_nop 0
	v_cndmask_b32_e64 v141, v137, v141, s[6:7]
	v_fma_f32 v137, -v142, v137, v136
	v_cmp_lt_f32_e64 s[6:7], 0, v137
	s_nop 1
	v_cndmask_b32_e64 v137, v141, v142, s[6:7]
	v_mul_f32_e32 v141, 0x37800000, v137
	v_cndmask_b32_e64 v137, v137, v141, s[0:1]
	v_cmp_class_f32_e64 s[0:1], v136, v180
	s_nop 1
	v_cndmask_b32_e64 v141, v137, v136, s[0:1]
	s_waitcnt vmcnt(1)
	v_mov_b32_e32 v136, v132
	s_waitcnt vmcnt(0)
	v_mov_b32_e32 v137, v128
	v_mov_b32_e32 v128, v133
	v_mov_b32_e32 v132, v134
	v_mov_b32_e32 v133, v130
	v_mov_b32_e32 v130, v135
	v_pk_add_f32 v[128:129], v[136:137], v[128:129]
	v_pk_add_f32 v[130:131], v[132:133], v[130:131]
	v_div_scale_f32 v142, s[0:1], v141, v141, 1.0
	v_pk_add_f32 v[128:129], v[128:129], v[130:131]
	v_rcp_f32_e32 v143, v142
	v_add_f32_e32 v128, v128, v129
	ds_bpermute_b32 v129, v171, v128
	v_div_fmas_f32 v130, v139, v151, v140
	v_div_fixup_f32 v131, v130, v149, 1.0
	v_fma_f32 v130, -v142, v143, 1.0
	v_fmac_f32_e32 v143, v130, v143
	s_waitcnt lgkmcnt(0)
	v_add_f32_e32 v128, v128, v129
	ds_bpermute_b32 v129, v214, v128
	v_div_scale_f32 v130, vcc, 1.0, v141, 1.0
	v_mul_f32_e32 v132, v130, v143
	v_fma_f32 v133, -v142, v132, v130
	s_waitcnt lgkmcnt(0)
	v_add_f32_e32 v128, v128, v129
	v_fmamk_f32 v128, v128, 0x3a000000, v179
	v_mul_f32_e32 v129, 0x4f800000, v128
	v_cmp_gt_f32_e64 s[0:1], s44, v128
	v_fmac_f32_e32 v132, v133, v143
	v_fma_f32 v130, -v142, v132, v130
	v_cndmask_b32_e64 v128, v128, v129, s[0:1]
	v_sqrt_f32_e32 v129, v128
	v_div_fmas_f32 v130, v130, v143, v132
	v_div_fixup_f32 v139, v130, v141, 1.0
	v_ashrrev_i32_e32 v171, 31, v170
	v_add_u32_e32 v133, -1, v129
	v_fma_f32 v134, -v133, v129, v128
	v_cmp_ge_f32_e64 s[6:7], 0, v134
	v_add_u32_e32 v134, 1, v129
	s_nop 0
	v_cndmask_b32_e64 v133, v129, v133, s[6:7]
	v_fma_f32 v129, -v134, v129, v128
	v_cmp_lt_f32_e64 s[6:7], 0, v129
	s_nop 1
	v_cndmask_b32_e64 v129, v133, v134, s[6:7]
	v_mul_f32_e32 v133, 0x37800000, v129
	v_cndmask_b32_e64 v129, v129, v133, s[0:1]
	v_cmp_class_f32_e64 s[0:1], v128, v180
	s_nop 1
	v_cndmask_b32_e64 v128, v129, v128, s[0:1]
	v_div_scale_f32 v129, s[0:1], v128, v128, 1.0
	v_rcp_f32_e32 v133, v129
	s_nop 0
	v_fma_f32 v130, -v129, v133, 1.0
	v_fmac_f32_e32 v133, v130, v133
	v_div_scale_f32 v130, vcc, 1.0, v128, 1.0
	v_mul_f32_e32 v132, v130, v133
	v_fma_f32 v134, -v129, v132, v130
	v_fmac_f32_e32 v132, v134, v133
	v_fma_f32 v129, -v129, v132, v130
	v_mul_f32_e32 v130, 0xbfb8aa3b, v160
	v_div_fmas_f32 v129, v129, v133, v132
	v_pk_mul_f32 v[136:137], v[124:125], v[130:131] op_sel_hi:[1,0]
	v_div_fixup_f32 v128, v129, v128, 1.0
	v_exp_f32_e32 v129, v136
	v_pk_mul_f32 v[134:135], v[126:127], v[130:131] op_sel_hi:[1,0]
	v_exp_f32_e32 v133, v137
	v_exp_f32_e32 v136, v134
	v_exp_f32_e32 v137, v135
	v_add_f32_e32 v129, 1.0, v129
	v_rcp_f32_e32 v134, v129
	v_add_f32_e32 v129, 1.0, v133
	v_rcp_f32_e32 v135, v129
	v_add_f32_e32 v129, 1.0, v136
	v_pk_mul_f32 v[126:127], v[116:117], v[130:131] op_sel_hi:[1,0]
	v_rcp_f32_e32 v136, v129
	v_add_f32_e32 v129, 1.0, v137
	v_pk_mul_f32 v[124:125], v[118:119], v[130:131] op_sel_hi:[1,0]
	v_exp_f32_e32 v126, v126
	v_exp_f32_e32 v127, v127
	v_rcp_f32_e32 v137, v129
	v_exp_f32_e32 v129, v124
	v_exp_f32_e32 v130, v125
	v_add_f32_e32 v124, 1.0, v126
	v_add_f32_e32 v125, 1.0, v127
	v_rcp_f32_e32 v124, v124
	v_rcp_f32_e32 v125, v125
	v_add_f32_e32 v126, 1.0, v129
	v_add_f32_e32 v127, 1.0, v130
	v_rcp_f32_e32 v126, v126
	v_rcp_f32_e32 v127, v127
	v_mul_f32_e32 v132, v160, v160
	v_pk_mul_f32 v[112:113], v[112:113], v[132:133] op_sel_hi:[1,0]
	v_pk_mul_f32 v[120:121], v[120:121], v[132:133] op_sel_hi:[1,0]
	v_pk_mul_f32 v[122:123], v[122:123], v[132:133] op_sel_hi:[1,0]
	v_pk_mul_f32 v[114:115], v[114:115], v[132:133] op_sel_hi:[1,0]
	v_pk_mul_f32 v[112:113], v[112:113], v[124:125]
	v_pk_mul_f32 v[122:123], v[122:123], v[136:137]
	v_pk_mul_f32 v[120:121], v[120:121], v[134:135]
	v_pk_mul_f32 v[114:115], v[114:115], v[126:127]
	v_cvt_pk_bf16_f32 v116, v120, v121
	v_cvt_pk_bf16_f32 v117, v122, v123
	v_cvt_pk_bf16_f32 v118, v112, v113
	v_mov_b64_e32 v[112:113], s[68:69]
	v_cvt_pk_bf16_f32 v119, v114, v115
	v_mad_i64_i32 v[120:121], s[0:1], v181, s45, v[112:113]
	v_lshlrev_b64 v[114:115], 1, v[170:171]
	v_lshl_add_u64 v[120:121], v[120:121], 0, v[114:115]
	global_store_dwordx4 v[120:121], v[116:119], off nt
	s_andn2_b64 vcc, exec, s[4:5]
	s_nop 0
	v_mul_f32_e32 v116, 0xbfb8aa3b, v188
	v_pk_mul_f32 v[122:123], v[108:109], v[116:117] op_sel_hi:[1,0]
	v_pk_mul_f32 v[120:121], v[110:111], v[116:117] op_sel_hi:[1,0]
	v_exp_f32_e32 v117, v122
	v_exp_f32_e32 v119, v123
	v_exp_f32_e32 v122, v120
	v_exp_f32_e32 v123, v121
	v_add_f32_e32 v117, 1.0, v117
	v_rcp_f32_e32 v120, v117
	v_add_f32_e32 v117, 1.0, v119
	v_rcp_f32_e32 v121, v117
	v_add_f32_e32 v117, 1.0, v122
	v_rcp_f32_e32 v122, v117
	v_add_f32_e32 v117, 1.0, v123
	v_pk_mul_f32 v[108:109], v[102:103], v[116:117] op_sel_hi:[1,0]
	v_pk_mul_f32 v[110:111], v[100:101], v[116:117] op_sel_hi:[1,0]
	v_rcp_f32_e32 v123, v117
	v_exp_f32_e32 v110, v110
	v_exp_f32_e32 v111, v111
	v_exp_f32_e32 v116, v108
	v_exp_f32_e32 v117, v109
	v_add_f32_e32 v108, 1.0, v110
	v_add_f32_e32 v109, 1.0, v111
	v_add_f32_e32 v110, 1.0, v116
	v_add_f32_e32 v111, 1.0, v117
	v_rcp_f32_e32 v108, v108
	v_rcp_f32_e32 v109, v109
	v_rcp_f32_e32 v110, v110
	v_rcp_f32_e32 v111, v111
	v_mul_f32_e32 v118, v188, v188
	v_pk_mul_f32 v[96:97], v[96:97], v[118:119] op_sel_hi:[1,0]
	v_pk_mul_f32 v[98:99], v[98:99], v[118:119] op_sel_hi:[1,0]
	v_pk_mul_f32 v[104:105], v[104:105], v[118:119] op_sel_hi:[1,0]
	v_pk_mul_f32 v[106:107], v[106:107], v[118:119] op_sel_hi:[1,0]
	v_pk_mul_f32 v[100:101], v[98:99], v[110:111]
	v_pk_mul_f32 v[98:99], v[96:97], v[108:109]
	v_add_u32_e32 v102, 16, v181
	v_pk_mul_f32 v[106:107], v[106:107], v[122:123]
	v_pk_mul_f32 v[104:105], v[104:105], v[120:121]
	s_nop 0
	v_cvt_pk_bf16_f32 v96, v104, v105
	v_cvt_pk_bf16_f32 v97, v106, v107
	v_cvt_pk_bf16_f32 v98, v98, v99
	v_cvt_pk_bf16_f32 v99, v100, v101
	v_mad_i64_i32 v[100:101], s[0:1], v102, s45, v[112:113]
	v_lshl_add_u64 v[100:101], v[100:101], 0, v[114:115]
	global_store_dwordx4 v[100:101], v[96:99], off nt
	s_nop 1
	v_mul_f32_e32 v96, 0xbfb8aa3b, v186
	v_pk_mul_f32 v[102:103], v[92:93], v[96:97] op_sel_hi:[1,0]
	v_pk_mul_f32 v[100:101], v[94:95], v[96:97] op_sel_hi:[1,0]
	v_exp_f32_e32 v97, v102
	v_exp_f32_e32 v99, v103
	v_exp_f32_e32 v102, v100
	v_exp_f32_e32 v103, v101
	v_add_f32_e32 v97, 1.0, v97
	v_rcp_f32_e32 v100, v97
	v_add_f32_e32 v97, 1.0, v99
	v_rcp_f32_e32 v101, v97
	v_add_f32_e32 v97, 1.0, v102
	v_rcp_f32_e32 v102, v97
	v_add_f32_e32 v97, 1.0, v103
	v_pk_mul_f32 v[92:93], v[86:87], v[96:97] op_sel_hi:[1,0]
	v_pk_mul_f32 v[94:95], v[84:85], v[96:97] op_sel_hi:[1,0]
	v_rcp_f32_e32 v103, v97
	v_exp_f32_e32 v94, v94
	v_exp_f32_e32 v95, v95
	v_exp_f32_e32 v96, v92
	v_exp_f32_e32 v97, v93
	v_add_f32_e32 v92, 1.0, v94
	v_add_f32_e32 v93, 1.0, v95
	v_add_f32_e32 v94, 1.0, v96
	v_add_f32_e32 v95, 1.0, v97
	v_rcp_f32_e32 v92, v92
	v_rcp_f32_e32 v93, v93
	v_rcp_f32_e32 v94, v94
	v_rcp_f32_e32 v95, v95
	v_mul_f32_e32 v98, v186, v186
	v_pk_mul_f32 v[80:81], v[80:81], v[98:99] op_sel_hi:[1,0]
	v_pk_mul_f32 v[82:83], v[82:83], v[98:99] op_sel_hi:[1,0]
	v_pk_mul_f32 v[88:89], v[88:89], v[98:99] op_sel_hi:[1,0]
	v_pk_mul_f32 v[90:91], v[90:91], v[98:99] op_sel_hi:[1,0]
	v_pk_mul_f32 v[84:85], v[82:83], v[94:95]
	v_pk_mul_f32 v[82:83], v[80:81], v[92:93]
	v_add_u32_e32 v86, 32, v181
	v_pk_mul_f32 v[90:91], v[90:91], v[102:103]
	v_pk_mul_f32 v[88:89], v[88:89], v[100:101]
	s_nop 0
	v_cvt_pk_bf16_f32 v80, v88, v89
	v_cvt_pk_bf16_f32 v81, v90, v91
	v_cvt_pk_bf16_f32 v82, v82, v83
	v_cvt_pk_bf16_f32 v83, v84, v85
	v_mad_i64_i32 v[84:85], s[0:1], v86, s45, v[112:113]
	v_lshl_add_u64 v[84:85], v[84:85], 0, v[114:115]
	global_store_dwordx4 v[84:85], v[80:83], off nt
	s_nop 1
	v_mul_f32_e32 v80, 0xbfb8aa3b, v146
	v_pk_mul_f32 v[86:87], v[76:77], v[80:81] op_sel_hi:[1,0]
	v_pk_mul_f32 v[84:85], v[78:79], v[80:81] op_sel_hi:[1,0]
	v_exp_f32_e32 v81, v86
	v_exp_f32_e32 v83, v87
	v_exp_f32_e32 v86, v84
	v_exp_f32_e32 v87, v85
	v_add_f32_e32 v81, 1.0, v81
	v_rcp_f32_e32 v84, v81
	v_add_f32_e32 v81, 1.0, v83
	v_rcp_f32_e32 v85, v81
	v_add_f32_e32 v81, 1.0, v86
	v_rcp_f32_e32 v86, v81
	v_add_f32_e32 v81, 1.0, v87
	v_pk_mul_f32 v[76:77], v[70:71], v[80:81] op_sel_hi:[1,0]
	v_pk_mul_f32 v[78:79], v[68:69], v[80:81] op_sel_hi:[1,0]
	v_rcp_f32_e32 v87, v81
	v_exp_f32_e32 v78, v78
	v_exp_f32_e32 v79, v79
	v_exp_f32_e32 v80, v76
	v_exp_f32_e32 v81, v77
	v_add_f32_e32 v76, 1.0, v78
	v_add_f32_e32 v77, 1.0, v79
	v_add_f32_e32 v78, 1.0, v80
	v_add_f32_e32 v79, 1.0, v81
	v_rcp_f32_e32 v76, v76
	v_rcp_f32_e32 v77, v77
	v_rcp_f32_e32 v78, v78
	v_rcp_f32_e32 v79, v79
	v_mul_f32_e32 v82, v146, v146
	v_pk_mul_f32 v[64:65], v[64:65], v[82:83] op_sel_hi:[1,0]
	v_pk_mul_f32 v[66:67], v[66:67], v[82:83] op_sel_hi:[1,0]
	v_pk_mul_f32 v[72:73], v[72:73], v[82:83] op_sel_hi:[1,0]
	v_pk_mul_f32 v[74:75], v[74:75], v[82:83] op_sel_hi:[1,0]
	v_pk_mul_f32 v[68:69], v[66:67], v[78:79]
	v_pk_mul_f32 v[66:67], v[64:65], v[76:77]
	v_add_u32_e32 v70, 48, v181
	v_pk_mul_f32 v[74:75], v[74:75], v[86:87]
	v_pk_mul_f32 v[72:73], v[72:73], v[84:85]
	s_nop 0
	v_cvt_pk_bf16_f32 v64, v72, v73
	v_cvt_pk_bf16_f32 v65, v74, v75
	v_cvt_pk_bf16_f32 v66, v66, v67
	v_cvt_pk_bf16_f32 v67, v68, v69
	v_mad_i64_i32 v[68:69], s[0:1], v70, s45, v[112:113]
	v_lshl_add_u64 v[68:69], v[68:69], 0, v[114:115]
	global_store_dwordx4 v[68:69], v[64:67], off nt
	s_nop 1
	v_add_u32_e32 v65, 0x80, v181
	v_mul_f32_e32 v64, 0xbfb8aa3b, v138
	v_pk_mul_f32 v[70:71], v[60:61], v[64:65] op_sel_hi:[1,0]
	v_pk_mul_f32 v[68:69], v[62:63], v[64:65] op_sel_hi:[1,0]
	v_exp_f32_e32 v67, v70
	v_exp_f32_e32 v70, v71
	v_exp_f32_e32 v71, v68
	v_exp_f32_e32 v72, v69
	v_add_f32_e32 v67, 1.0, v67
	v_rcp_f32_e32 v68, v67
	v_add_f32_e32 v67, 1.0, v70
	v_rcp_f32_e32 v69, v67
	v_add_f32_e32 v67, 1.0, v71
	v_mul_f32_e32 v66, v138, v138
	v_rcp_f32_e32 v70, v67
	v_add_f32_e32 v67, 1.0, v72
	v_pk_mul_f32 v[60:61], v[54:55], v[64:65] op_sel_hi:[1,0]
	v_pk_mul_f32 v[62:63], v[52:53], v[64:65] op_sel_hi:[1,0]
	v_rcp_f32_e32 v71, v67
	v_pk_mul_f32 v[56:57], v[56:57], v[66:67] op_sel_hi:[1,0]
	v_pk_mul_f32 v[58:59], v[58:59], v[66:67] op_sel_hi:[1,0]
	v_exp_f32_e32 v62, v62
	v_exp_f32_e32 v63, v63
	v_exp_f32_e32 v64, v60
	v_exp_f32_e32 v67, v61
	v_add_f32_e32 v60, 1.0, v62
	v_add_f32_e32 v61, 1.0, v63
	v_add_f32_e32 v62, 1.0, v64
	v_add_f32_e32 v63, 1.0, v67
	v_rcp_f32_e32 v60, v60
	v_rcp_f32_e32 v61, v61
	v_rcp_f32_e32 v62, v62
	v_rcp_f32_e32 v63, v63
	v_pk_mul_f32 v[48:49], v[48:49], v[66:67] op_sel_hi:[1,0]
	v_pk_mul_f32 v[50:51], v[50:51], v[66:67] op_sel_hi:[1,0]
	v_pk_mul_f32 v[58:59], v[58:59], v[70:71]
	v_pk_mul_f32 v[52:53], v[50:51], v[62:63]
	v_pk_mul_f32 v[50:51], v[48:49], v[60:61]
	v_pk_mul_f32 v[56:57], v[56:57], v[68:69]
	s_nop 0
	v_cvt_pk_bf16_f32 v48, v56, v57
	v_cvt_pk_bf16_f32 v49, v58, v59
	v_cvt_pk_bf16_f32 v50, v50, v51
	v_cvt_pk_bf16_f32 v51, v52, v53
	v_mad_i64_i32 v[52:53], s[0:1], v65, s45, v[112:113]
	v_lshl_add_u64 v[52:53], v[52:53], 0, v[114:115]
	global_store_dwordx4 v[52:53], v[48:51], off nt
	s_nop 1
	v_mul_f32_e32 v48, 0xbfb8aa3b, v131
	v_pk_mul_f32 v[54:55], v[44:45], v[48:49] op_sel_hi:[1,0]
	v_pk_mul_f32 v[52:53], v[46:47], v[48:49] op_sel_hi:[1,0]
	v_exp_f32_e32 v49, v54
	v_exp_f32_e32 v51, v55
	v_exp_f32_e32 v54, v52
	v_exp_f32_e32 v55, v53
	v_add_f32_e32 v49, 1.0, v49
	v_rcp_f32_e32 v52, v49
	v_add_f32_e32 v49, 1.0, v51
	v_rcp_f32_e32 v53, v49
	v_add_f32_e32 v49, 1.0, v54
	v_rcp_f32_e32 v54, v49
	v_add_f32_e32 v49, 1.0, v55
	v_pk_mul_f32 v[44:45], v[38:39], v[48:49] op_sel_hi:[1,0]
	v_pk_mul_f32 v[46:47], v[36:37], v[48:49] op_sel_hi:[1,0]
	v_rcp_f32_e32 v55, v49
	v_exp_f32_e32 v46, v46
	v_exp_f32_e32 v47, v47
	v_exp_f32_e32 v48, v44
	v_exp_f32_e32 v49, v45
	v_add_f32_e32 v44, 1.0, v46
	v_add_f32_e32 v45, 1.0, v47
	v_add_f32_e32 v46, 1.0, v48
	v_add_f32_e32 v47, 1.0, v49
	v_rcp_f32_e32 v44, v44
	v_rcp_f32_e32 v45, v45
	v_rcp_f32_e32 v46, v46
	v_rcp_f32_e32 v47, v47
	v_mul_f32_e32 v50, v131, v131
	v_pk_mul_f32 v[32:33], v[32:33], v[50:51] op_sel_hi:[1,0]
	v_pk_mul_f32 v[34:35], v[34:35], v[50:51] op_sel_hi:[1,0]
	v_pk_mul_f32 v[40:41], v[40:41], v[50:51] op_sel_hi:[1,0]
	v_pk_mul_f32 v[42:43], v[42:43], v[50:51] op_sel_hi:[1,0]
	v_pk_mul_f32 v[36:37], v[34:35], v[46:47]
	v_pk_mul_f32 v[34:35], v[32:33], v[44:45]
	v_add_u32_e32 v38, 0x90, v181
	v_pk_mul_f32 v[42:43], v[42:43], v[54:55]
	v_pk_mul_f32 v[40:41], v[40:41], v[52:53]
	s_nop 0
	v_cvt_pk_bf16_f32 v32, v40, v41
	v_cvt_pk_bf16_f32 v33, v42, v43
	v_cvt_pk_bf16_f32 v34, v34, v35
	v_cvt_pk_bf16_f32 v35, v36, v37
	v_mad_i64_i32 v[36:37], s[0:1], v38, s45, v[112:113]
	v_lshl_add_u64 v[36:37], v[36:37], 0, v[114:115]
	global_store_dwordx4 v[36:37], v[32:35], off nt
	s_nop 1
	v_mul_f32_e32 v32, 0xbfb8aa3b, v139
	v_pk_mul_f32 v[38:39], v[28:29], v[32:33] op_sel_hi:[1,0]
	v_pk_mul_f32 v[36:37], v[30:31], v[32:33] op_sel_hi:[1,0]
	v_exp_f32_e32 v33, v38
	v_exp_f32_e32 v35, v39
	v_exp_f32_e32 v38, v36
	v_exp_f32_e32 v39, v37
	v_add_f32_e32 v33, 1.0, v33
	v_rcp_f32_e32 v36, v33
	v_add_f32_e32 v33, 1.0, v35
	v_rcp_f32_e32 v37, v33
	v_add_f32_e32 v33, 1.0, v38
	v_rcp_f32_e32 v38, v33
	v_add_f32_e32 v33, 1.0, v39
	v_pk_mul_f32 v[28:29], v[22:23], v[32:33] op_sel_hi:[1,0]
	v_pk_mul_f32 v[30:31], v[20:21], v[32:33] op_sel_hi:[1,0]
	v_rcp_f32_e32 v39, v33
	v_exp_f32_e32 v30, v30
	v_exp_f32_e32 v31, v31
	v_exp_f32_e32 v32, v28
	v_exp_f32_e32 v33, v29
	v_add_f32_e32 v28, 1.0, v30
	v_add_f32_e32 v29, 1.0, v31
	v_add_f32_e32 v30, 1.0, v32
	v_add_f32_e32 v31, 1.0, v33
	v_rcp_f32_e32 v28, v28
	v_rcp_f32_e32 v29, v29
	v_rcp_f32_e32 v30, v30
	v_rcp_f32_e32 v31, v31
	v_mul_f32_e32 v34, v139, v139
	v_pk_mul_f32 v[16:17], v[16:17], v[34:35] op_sel_hi:[1,0]
	v_pk_mul_f32 v[18:19], v[18:19], v[34:35] op_sel_hi:[1,0]
	v_pk_mul_f32 v[24:25], v[24:25], v[34:35] op_sel_hi:[1,0]
	v_pk_mul_f32 v[26:27], v[26:27], v[34:35] op_sel_hi:[1,0]
	v_pk_mul_f32 v[20:21], v[18:19], v[30:31]
	v_pk_mul_f32 v[18:19], v[16:17], v[28:29]
	v_add_u32_e32 v22, 0xa0, v181
	v_pk_mul_f32 v[26:27], v[26:27], v[38:39]
	v_pk_mul_f32 v[24:25], v[24:25], v[36:37]
	s_nop 0
	v_cvt_pk_bf16_f32 v16, v24, v25
	v_cvt_pk_bf16_f32 v17, v26, v27
	v_cvt_pk_bf16_f32 v18, v18, v19
	v_cvt_pk_bf16_f32 v19, v20, v21
	v_mad_i64_i32 v[20:21], s[0:1], v22, s45, v[112:113]
	v_lshl_add_u64 v[20:21], v[20:21], 0, v[114:115]
	global_store_dwordx4 v[20:21], v[16:19], off nt
	s_nop 1
	v_mul_f32_e32 v16, 0xbfb8aa3b, v128
	v_pk_mul_f32 v[22:23], v[12:13], v[16:17] op_sel_hi:[1,0]
	v_pk_mul_f32 v[20:21], v[14:15], v[16:17] op_sel_hi:[1,0]
	v_exp_f32_e32 v17, v22
	v_exp_f32_e32 v19, v23
	v_exp_f32_e32 v22, v20
	v_exp_f32_e32 v23, v21
	v_add_f32_e32 v17, 1.0, v17
	v_rcp_f32_e32 v20, v17
	v_add_f32_e32 v17, 1.0, v19
	v_rcp_f32_e32 v21, v17
	v_add_f32_e32 v17, 1.0, v22
	v_rcp_f32_e32 v22, v17
	v_add_f32_e32 v17, 1.0, v23
	v_pk_mul_f32 v[12:13], v[6:7], v[16:17] op_sel_hi:[1,0]
	v_pk_mul_f32 v[14:15], v[4:5], v[16:17] op_sel_hi:[1,0]
	v_rcp_f32_e32 v23, v17
	v_exp_f32_e32 v14, v14
	v_exp_f32_e32 v15, v15
	v_exp_f32_e32 v16, v12
	v_exp_f32_e32 v17, v13
	v_add_f32_e32 v12, 1.0, v14
	v_add_f32_e32 v13, 1.0, v15
	v_add_f32_e32 v14, 1.0, v16
	v_add_f32_e32 v15, 1.0, v17
	v_rcp_f32_e32 v12, v12
	v_rcp_f32_e32 v13, v13
	v_rcp_f32_e32 v14, v14
	v_rcp_f32_e32 v15, v15
	v_mul_f32_e32 v18, v128, v128
	v_pk_mul_f32 v[0:1], v[0:1], v[18:19] op_sel_hi:[1,0]
	v_pk_mul_f32 v[2:3], v[2:3], v[18:19] op_sel_hi:[1,0]
	v_pk_mul_f32 v[8:9], v[8:9], v[18:19] op_sel_hi:[1,0]
	v_pk_mul_f32 v[10:11], v[10:11], v[18:19] op_sel_hi:[1,0]
	v_pk_mul_f32 v[4:5], v[2:3], v[14:15]
	v_pk_mul_f32 v[2:3], v[0:1], v[12:13]
	v_add_u32_e32 v6, 0xb0, v181
	v_pk_mul_f32 v[10:11], v[10:11], v[22:23]
	v_pk_mul_f32 v[8:9], v[8:9], v[20:21]
	s_nop 0
	v_cvt_pk_bf16_f32 v0, v8, v9
	v_cvt_pk_bf16_f32 v1, v10, v11
	v_cvt_pk_bf16_f32 v2, v2, v3
	v_cvt_pk_bf16_f32 v3, v4, v5
	v_mad_i64_i32 v[4:5], s[0:1], v6, s45, v[112:113]
	v_lshl_add_u64 v[4:5], v[4:5], 0, v[114:115]
	s_mov_b64 s[0:1], -1
	global_store_dwordx4 v[4:5], v[0:3], off nt
	s_cbranch_vccnz .LBB0_628
	s_andn2_b64 vcc, exec, s[8:9]
	s_cbranch_vccnz .LBB0_627
	s_barrier
	s_branch .LBB0_627

.LBB0_1367:
	v_mov_b32_e32 v128, v173
	v_mov_b32_e32 v129, v172
	s_lshl_b32 s0, s0, 8
	s_add_i32 s0, s0, s35
	v_lshlrev_b32_e32 v144, 3, v128
	v_add_u32_e32 v181, s0, v129
	v_ashrrev_i32_e32 v145, 31, v144
	v_lshlrev_b32_e32 v160, 5, v181
	v_lshl_add_u64 v[182:183], v[144:145], 2, s[76:77]
	v_lshl_add_u64 v[132:133], v[160:161], 2, v[182:183]
	v_add_u32_e32 v136, 0x200, v160
	v_mov_b32_e32 v137, v161
	global_load_dwordx4 v[128:131], v[132:133], off
	s_nop 0
	global_load_dwordx4 v[132:135], v[132:133], off offset:16
	v_lshl_add_u64 v[140:141], v[136:137], 2, v[182:183]
	global_load_dwordx4 v[136:139], v[140:141], off
	s_nop 0
	global_load_dwordx4 v[140:143], v[140:141], off offset:16
	v_and_b32_e32 v148, 64, v178
	s_lshl_b32 s0, s1, 7
	v_xor_b32_e32 v146, 16, v178
	v_add_u32_e32 v148, 64, v148
	s_or_b32 s0, s0, s36
	v_cmp_lt_i32_e32 vcc, v146, v148
	v_mov_b32_e32 v145, v161
	v_add_u32_e32 v170, s0, v144
	v_cndmask_b32_e32 v146, v178, v146, vcc
	v_add_u32_e32 v144, 0x400, v160
	v_mov_b32_e32 v147, v161
	v_mov_b32_e32 v187, v161
	v_lshlrev_b32_e32 v171, 2, v146
	v_add_u32_e32 v146, 0x600, v160
	v_add_u32_e32 v186, 0x1400, v160
	v_lshl_add_u64 v[144:145], v[144:145], 2, v[182:183]
	v_lshl_add_u64 v[146:147], v[146:147], 2, v[182:183]
	v_lshl_add_u64 v[212:213], v[186:187], 2, v[182:183]
	global_load_dwordx4 v[186:189], v[144:145], off
	global_load_dwordx4 v[190:193], v[144:145], off offset:16
	global_load_dwordx4 v[194:197], v[146:147], off
	global_load_dwordx4 v[198:201], v[146:147], off offset:16
	v_xor_b32_e32 v150, 32, v178
	v_cmp_lt_i32_e32 vcc, v150, v148
	v_mov_b32_e32 v149, v161
	v_mov_b32_e32 v151, v161
	v_cndmask_b32_e32 v148, v178, v150, vcc
	v_lshlrev_b32_e32 v185, 2, v148
	v_add_u32_e32 v148, 0x1000, v160
	v_add_u32_e32 v150, 0x1200, v160
	v_add_u32_e32 v160, 0x1600, v160
	v_lshl_add_u64 v[148:149], v[148:149], 2, v[182:183]
	v_lshl_add_u64 v[210:211], v[150:151], 2, v[182:183]
	v_pk_mul_f32 v[122:123], v[126:127], v[122:123]
	v_pk_mul_f32 v[120:121], v[124:125], v[120:121]
	v_pk_mul_f32 v[112:113], v[116:117], v[112:113]
	v_pk_mul_f32 v[114:115], v[118:119], v[114:115]
	v_pk_mul_f32 v[106:107], v[110:111], v[106:107]
	v_pk_mul_f32 v[104:105], v[108:109], v[104:105]
	v_pk_mul_f32 v[98:99], v[102:103], v[98:99]
	v_pk_mul_f32 v[96:97], v[100:101], v[96:97]
	v_pk_mul_f32 v[90:91], v[94:95], v[90:91]
	v_pk_mul_f32 v[88:89], v[92:93], v[88:89]
	v_pk_mul_f32 v[82:83], v[86:87], v[82:83]
	v_pk_mul_f32 v[80:81], v[84:85], v[80:81]
	v_pk_mul_f32 v[74:75], v[78:79], v[74:75]
	v_pk_mul_f32 v[72:73], v[76:77], v[72:73]
	v_pk_mul_f32 v[66:67], v[70:71], v[66:67]
	v_pk_mul_f32 v[64:65], v[68:69], v[64:65]
	v_pk_mul_f32 v[58:59], v[62:63], v[58:59]
	v_pk_mul_f32 v[56:57], v[60:61], v[56:57]
	v_pk_mul_f32 v[50:51], v[54:55], v[50:51]
	v_pk_mul_f32 v[48:49], v[52:53], v[48:49]
	v_pk_mul_f32 v[42:43], v[46:47], v[42:43]
	v_pk_mul_f32 v[40:41], v[44:45], v[40:41]
	v_pk_mul_f32 v[34:35], v[38:39], v[34:35]
	v_pk_mul_f32 v[32:33], v[36:37], v[32:33]
	v_pk_mul_f32 v[26:27], v[30:31], v[26:27]
	v_pk_mul_f32 v[24:25], v[28:29], v[24:25]
	v_pk_mul_f32 v[18:19], v[22:23], v[18:19]
	v_pk_mul_f32 v[16:17], v[20:21], v[16:17]
	v_pk_mul_f32 v[10:11], v[14:15], v[10:11]
	v_pk_mul_f32 v[8:9], v[12:13], v[8:9]
	v_pk_mul_f32 v[2:3], v[6:7], v[2:3]
	v_pk_mul_f32 v[0:1], v[4:5], v[0:1]
	s_waitcnt vmcnt(0)
	v_mov_b32_e32 v144, v128
	v_mov_b32_e32 v145, v132
	v_mov_b32_e32 v132, v129
	v_mov_b32_e32 v128, v130
	v_mov_b32_e32 v129, v134
	v_mov_b32_e32 v134, v131
	v_mov_b32_e32 v130, v136
	v_mov_b32_e32 v131, v140
	v_mov_b32_e32 v140, v137
	v_mov_b32_e32 v136, v138
	v_mov_b32_e32 v137, v142
	v_mov_b32_e32 v142, v139
	v_pk_add_f32 v[132:133], v[144:145], v[132:133]
	v_pk_add_f32 v[128:129], v[128:129], v[134:135]
	v_pk_add_f32 v[130:131], v[130:131], v[140:141]
	v_pk_add_f32 v[134:135], v[136:137], v[142:143]
	v_pk_add_f32 v[128:129], v[132:133], v[128:129]
	v_pk_add_f32 v[130:131], v[130:131], v[134:135]
	v_add_f32_e32 v128, v128, v129
	v_add_f32_e32 v129, v130, v131
	ds_bpermute_b32 v130, v171, v128
	ds_bpermute_b32 v131, v171, v129
	global_load_dwordx4 v[202:205], v[148:149], off
	global_load_dwordx4 v[206:209], v[148:149], off offset:16
	s_nop 0
	global_load_dwordx4 v[148:151], v[210:211], off
	global_load_dwordx4 v[144:147], v[210:211], off offset:16
	global_load_dwordx4 v[140:143], v[212:213], off
	global_load_dwordx4 v[136:139], v[212:213], off offset:16
	s_waitcnt lgkmcnt(1)
	v_add_f32_e32 v130, v128, v130
	ds_bpermute_b32 v132, v185, v130
	s_waitcnt lgkmcnt(1)
	v_add_f32_e32 v131, v129, v131
	v_lshl_add_u64 v[128:129], v[160:161], 2, v[182:183]
	ds_bpermute_b32 v133, v185, v131
	s_waitcnt lgkmcnt(1)
	v_add_f32_e32 v130, v130, v132
	v_fmamk_f32 v130, v130, 0x3a000000, v179
	v_mul_f32_e32 v132, 0x4f800000, v130
	v_cmp_gt_f32_e32 vcc, s43, v130
	s_waitcnt lgkmcnt(0)
	v_add_f32_e32 v131, v131, v133
	v_fmamk_f32 v131, v131, 0x3a000000, v179
	v_cndmask_b32_e32 v160, v130, v132, vcc
	v_sqrt_f32_e32 v183, v160
	v_mul_f32_e32 v133, 0x4f800000, v131
	v_cmp_gt_f32_e64 s[0:1], s43, v131
	v_add_u32_e32 v211, -1, v183
	v_add_u32_e32 v212, 1, v183
	v_fma_f32 v215, -v211, v183, v160
	v_fma_f32 v216, -v212, v183, v160
	v_cmp_ge_f32_e64 s[6:7], 0, v215
	v_cndmask_b32_e64 v182, v131, v133, s[0:1]
	v_sqrt_f32_e32 v210, v182
	v_cndmask_b32_e64 v183, v183, v211, s[6:7]
	v_cmp_lt_f32_e64 s[6:7], 0, v216
	global_load_dwordx4 v[132:135], v[128:129], off
	s_nop 0
	global_load_dwordx4 v[128:131], v[128:129], off offset:16
	v_cndmask_b32_e64 v183, v183, v212, s[6:7]
	v_mul_f32_e32 v211, 0x37800000, v183
	v_cndmask_b32_e32 v183, v183, v211, vcc
	v_cmp_class_f32_e32 vcc, v160, v180
	v_add_u32_e32 v213, -1, v210
	v_fma_f32 v217, -v213, v210, v182
	v_cndmask_b32_e32 v160, v183, v160, vcc
	v_div_scale_f32 v183, s[6:7], v160, v160, 1.0
	v_rcp_f32_e32 v211, v183
	v_add_u32_e32 v214, 1, v210
	v_cmp_ge_f32_e32 vcc, 0, v217
	v_fma_f32 v218, -v214, v210, v182
	v_cmp_lt_f32_e64 s[6:7], 0, v218
	v_cndmask_b32_e32 v210, v210, v213, vcc
	v_fma_f32 v213, -v183, v211, 1.0
	v_div_scale_f32 v212, vcc, 1.0, v160, 1.0
	v_fmac_f32_e32 v211, v213, v211
	v_mul_f32_e32 v213, v212, v211
	v_fma_f32 v215, -v183, v213, v212
	v_fmac_f32_e32 v213, v215, v211
	v_fma_f32 v212, -v183, v213, v212
	v_cndmask_b32_e64 v183, v210, v214, s[6:7]
	v_mul_f32_e32 v210, 0x37800000, v183
	v_cndmask_b32_e64 v183, v183, v210, s[0:1]
	v_cmp_class_f32_e64 s[0:1], v182, v180
	s_nop 1
	v_cndmask_b32_e64 v210, v183, v182, s[0:1]
	v_mov_b32_e32 v182, v186
	v_mov_b32_e32 v183, v190
	v_mov_b32_e32 v190, v187
	v_mov_b32_e32 v186, v188
	v_mov_b32_e32 v187, v192
	v_mov_b32_e32 v192, v189
	v_pk_add_f32 v[182:183], v[182:183], v[190:191]
	v_pk_add_f32 v[186:187], v[186:187], v[192:193]
	v_div_scale_f32 v214, s[0:1], v210, v210, 1.0
	v_pk_add_f32 v[182:183], v[182:183], v[186:187]
	v_rcp_f32_e32 v215, v214
	v_add_f32_e32 v182, v182, v183
	ds_bpermute_b32 v183, v171, v182
	v_div_fmas_f32 v186, v212, v211, v213
	v_div_fixup_f32 v160, v186, v160, 1.0
	v_fma_f32 v186, -v214, v215, 1.0
	v_fmac_f32_e32 v215, v186, v215
	s_waitcnt lgkmcnt(0)
	v_add_f32_e32 v182, v182, v183
	ds_bpermute_b32 v183, v185, v182
	v_div_scale_f32 v186, vcc, 1.0, v210, 1.0
	v_mul_f32_e32 v188, v186, v215
	v_fma_f32 v187, -v214, v188, v186
	s_waitcnt lgkmcnt(0)
	v_add_f32_e32 v182, v182, v183
	v_fmamk_f32 v182, v182, 0x3a000000, v179
	v_mul_f32_e32 v183, 0x4f800000, v182
	v_cmp_gt_f32_e64 s[0:1], s43, v182
	v_fmac_f32_e32 v188, v187, v215
	v_fma_f32 v189, -v214, v188, v186
	v_cndmask_b32_e64 v182, v182, v183, s[0:1]
	v_sqrt_f32_e32 v183, v182
	s_nop 0
	v_add_u32_e32 v186, -1, v183
	v_fma_f32 v187, -v186, v183, v182
	v_cmp_ge_f32_e64 s[6:7], 0, v187
	v_add_u32_e32 v187, 1, v183
	s_nop 0
	v_cndmask_b32_e64 v186, v183, v186, s[6:7]
	v_fma_f32 v183, -v187, v183, v182
	v_cmp_lt_f32_e64 s[6:7], 0, v183
	s_nop 1
	v_cndmask_b32_e64 v183, v186, v187, s[6:7]
	v_mul_f32_e32 v186, 0x37800000, v183
	v_cndmask_b32_e64 v183, v183, v186, s[0:1]
	v_cmp_class_f32_e64 s[0:1], v182, v180
	v_mov_b32_e32 v186, v196
	v_mov_b32_e32 v187, v200
	v_cndmask_b32_e64 v190, v183, v182, s[0:1]
	v_mov_b32_e32 v182, v194
	v_mov_b32_e32 v183, v198
	v_mov_b32_e32 v198, v195
	v_mov_b32_e32 v200, v197
	v_pk_add_f32 v[182:183], v[182:183], v[198:199]
	v_pk_add_f32 v[186:187], v[186:187], v[200:201]
	v_div_scale_f32 v191, s[0:1], v190, v190, 1.0
	v_pk_add_f32 v[182:183], v[182:183], v[186:187]
	v_rcp_f32_e32 v192, v191
	v_add_f32_e32 v182, v182, v183
	ds_bpermute_b32 v183, v171, v182
	v_div_fmas_f32 v186, v189, v215, v188
	v_div_fixup_f32 v188, v186, v210, 1.0
	v_fma_f32 v186, -v191, v192, 1.0
	v_fmac_f32_e32 v192, v186, v192
	s_waitcnt lgkmcnt(0)
	v_add_f32_e32 v182, v182, v183
	ds_bpermute_b32 v183, v185, v182
	v_div_scale_f32 v186, vcc, 1.0, v190, 1.0
	v_mul_f32_e32 v189, v186, v192
	v_fma_f32 v187, -v191, v189, v186
	s_waitcnt lgkmcnt(0)
	v_add_f32_e32 v182, v182, v183
	v_fmamk_f32 v182, v182, 0x3a000000, v179
	v_mul_f32_e32 v183, 0x4f800000, v182
	v_cmp_gt_f32_e64 s[0:1], s43, v182
	v_fmac_f32_e32 v189, v187, v192
	v_fma_f32 v191, -v191, v189, v186
	v_cndmask_b32_e64 v182, v182, v183, s[0:1]
	v_sqrt_f32_e32 v183, v182
	s_nop 0
	v_add_u32_e32 v186, -1, v183
	v_fma_f32 v187, -v186, v183, v182
	v_cmp_ge_f32_e64 s[6:7], 0, v187
	v_add_u32_e32 v187, 1, v183
	s_nop 0
	v_cndmask_b32_e64 v186, v183, v186, s[6:7]
	v_fma_f32 v183, -v187, v183, v182
	v_cmp_lt_f32_e64 s[6:7], 0, v183
	s_nop 1
	v_cndmask_b32_e64 v183, v186, v187, s[6:7]
	v_mul_f32_e32 v186, 0x37800000, v183
	v_cndmask_b32_e64 v183, v183, v186, s[0:1]
	v_cmp_class_f32_e64 s[0:1], v182, v180
	s_waitcnt vmcnt(7)
	v_mov_b32_e32 v186, v204
	s_waitcnt vmcnt(6)
	v_mov_b32_e32 v187, v208
	v_cndmask_b32_e64 v193, v183, v182, s[0:1]
	v_mov_b32_e32 v182, v202
	v_mov_b32_e32 v183, v206
	v_mov_b32_e32 v206, v203
	v_mov_b32_e32 v208, v205
	v_pk_add_f32 v[182:183], v[182:183], v[206:207]
	v_pk_add_f32 v[186:187], v[186:187], v[208:209]
	v_div_scale_f32 v194, s[0:1], v193, v193, 1.0
	v_pk_add_f32 v[182:183], v[182:183], v[186:187]
	v_rcp_f32_e32 v195, v194
	v_add_f32_e32 v182, v182, v183
	ds_bpermute_b32 v183, v171, v182
	v_div_fmas_f32 v186, v191, v192, v189
	v_fma_f32 v187, -v194, v195, 1.0
	v_fmac_f32_e32 v195, v187, v195
	v_div_scale_f32 v187, vcc, 1.0, v193, 1.0
	s_waitcnt lgkmcnt(0)
	v_add_f32_e32 v182, v182, v183
	ds_bpermute_b32 v183, v185, v182
	v_mul_f32_e32 v189, v187, v195
	v_div_fixup_f32 v186, v186, v190, 1.0
	v_fma_f32 v190, -v194, v189, v187
	v_fmac_f32_e32 v189, v190, v195
	s_waitcnt lgkmcnt(0)
	v_add_f32_e32 v182, v182, v183
	v_fmamk_f32 v182, v182, 0x3a000000, v179
	v_mul_f32_e32 v183, 0x4f800000, v182
	v_cmp_gt_f32_e64 s[0:1], s43, v182
	v_fma_f32 v187, -v194, v189, v187
	s_nop 0
	v_cndmask_b32_e64 v182, v182, v183, s[0:1]
	v_sqrt_f32_e32 v183, v182
	s_nop 0
	v_add_u32_e32 v190, -1, v183
	v_fma_f32 v191, -v190, v183, v182
	v_cmp_ge_f32_e64 s[6:7], 0, v191
	v_add_u32_e32 v191, 1, v183
	s_nop 0
	v_cndmask_b32_e64 v190, v183, v190, s[6:7]
	v_fma_f32 v183, -v191, v183, v182
	v_cmp_lt_f32_e64 s[6:7], 0, v183
	s_nop 1
	v_cndmask_b32_e64 v183, v190, v191, s[6:7]
	v_mul_f32_e32 v190, 0x37800000, v183
	v_cndmask_b32_e64 v183, v183, v190, s[0:1]
	v_cmp_class_f32_e64 s[0:1], v182, v180
	s_nop 1
	v_cndmask_b32_e64 v190, v183, v182, s[0:1]
	s_waitcnt vmcnt(5)
	v_mov_b32_e32 v182, v148
	s_waitcnt vmcnt(4)
	v_mov_b32_e32 v183, v144
	v_mov_b32_e32 v144, v149
	v_mov_b32_e32 v148, v150
	v_mov_b32_e32 v149, v146
	v_mov_b32_e32 v146, v151
	v_pk_add_f32 v[144:145], v[182:183], v[144:145]
	v_pk_add_f32 v[146:147], v[148:149], v[146:147]
	v_div_scale_f32 v191, s[0:1], v190, v190, 1.0
	v_pk_add_f32 v[144:145], v[144:145], v[146:147]
	v_rcp_f32_e32 v192, v191
	v_add_f32_e32 v144, v144, v145
	ds_bpermute_b32 v145, v171, v144
	v_div_fmas_f32 v146, v187, v195, v189
	v_fma_f32 v147, -v191, v192, 1.0
	v_fmac_f32_e32 v192, v147, v192
	v_div_scale_f32 v147, vcc, 1.0, v190, 1.0
	s_waitcnt lgkmcnt(0)
	v_add_f32_e32 v144, v144, v145
	ds_bpermute_b32 v145, v185, v144
	v_mul_f32_e32 v148, v147, v192
	v_fma_f32 v149, -v191, v148, v147
	v_fmac_f32_e32 v148, v149, v192
	v_fma_f32 v147, -v191, v148, v147
	s_waitcnt lgkmcnt(0)
	v_add_f32_e32 v144, v144, v145
	v_fmamk_f32 v144, v144, 0x3a000000, v179
	v_mul_f32_e32 v145, 0x4f800000, v144
	v_cmp_gt_f32_e64 s[0:1], s43, v144
	v_div_fixup_f32 v146, v146, v193, 1.0
	s_nop 0
	v_cndmask_b32_e64 v144, v144, v145, s[0:1]
	v_sqrt_f32_e32 v145, v144
	s_nop 0
	v_add_u32_e32 v149, -1, v145
	v_fma_f32 v150, -v149, v145, v144
	v_cmp_ge_f32_e64 s[6:7], 0, v150
	v_add_u32_e32 v150, 1, v145
	s_nop 0
	v_cndmask_b32_e64 v149, v145, v149, s[6:7]
	v_fma_f32 v145, -v150, v145, v144
	v_cmp_lt_f32_e64 s[6:7], 0, v145
	s_nop 1
	v_cndmask_b32_e64 v145, v149, v150, s[6:7]
	v_mul_f32_e32 v149, 0x37800000, v145
	v_cndmask_b32_e64 v145, v145, v149, s[0:1]
	v_cmp_class_f32_e64 s[0:1], v144, v180
	s_nop 1
	v_cndmask_b32_e64 v149, v145, v144, s[0:1]
	s_waitcnt vmcnt(3)
	v_mov_b32_e32 v144, v140
	s_waitcnt vmcnt(2)
	v_mov_b32_e32 v145, v136
	v_mov_b32_e32 v136, v141
	v_mov_b32_e32 v140, v142
	v_mov_b32_e32 v141, v138
	v_mov_b32_e32 v138, v143
	v_pk_add_f32 v[136:137], v[144:145], v[136:137]
	v_pk_add_f32 v[138:139], v[140:141], v[138:139]
	v_div_scale_f32 v150, s[0:1], v149, v149, 1.0
	v_pk_add_f32 v[136:137], v[136:137], v[138:139]
	v_rcp_f32_e32 v151, v150
	v_add_f32_e32 v136, v136, v137
	ds_bpermute_b32 v137, v171, v136
	v_div_fmas_f32 v138, v147, v192, v148
	v_fma_f32 v139, -v150, v151, 1.0
	v_fmac_f32_e32 v151, v139, v151
	v_div_scale_f32 v139, vcc, 1.0, v149, 1.0
	s_waitcnt lgkmcnt(0)
	v_add_f32_e32 v136, v136, v137
	ds_bpermute_b32 v137, v185, v136
	v_mul_f32_e32 v140, v139, v151
	v_fma_f32 v141, -v150, v140, v139
	v_fmac_f32_e32 v140, v141, v151
	v_fma_f32 v139, -v150, v140, v139
	s_waitcnt lgkmcnt(0)
	v_add_f32_e32 v136, v136, v137
	v_fmamk_f32 v136, v136, 0x3a000000, v179
	v_mul_f32_e32 v137, 0x4f800000, v136
	v_cmp_gt_f32_e64 s[0:1], s43, v136
	v_div_fixup_f32 v138, v138, v190, 1.0
	s_nop 0
	v_cndmask_b32_e64 v136, v136, v137, s[0:1]
	v_sqrt_f32_e32 v137, v136
	s_nop 0
	v_add_u32_e32 v141, -1, v137
	v_fma_f32 v142, -v141, v137, v136
	v_cmp_ge_f32_e64 s[6:7], 0, v142
	v_add_u32_e32 v142, 1, v137
	s_nop 0
	v_cndmask_b32_e64 v141, v137, v141, s[6:7]
	v_fma_f32 v137, -v142, v137, v136
	v_cmp_lt_f32_e64 s[6:7], 0, v137
	s_nop 1
	v_cndmask_b32_e64 v137, v141, v142, s[6:7]
	v_mul_f32_e32 v141, 0x37800000, v137
	v_cndmask_b32_e64 v137, v137, v141, s[0:1]
	v_cmp_class_f32_e64 s[0:1], v136, v180
	s_nop 1
	v_cndmask_b32_e64 v141, v137, v136, s[0:1]
	s_waitcnt vmcnt(1)
	v_mov_b32_e32 v136, v132
	s_waitcnt vmcnt(0)
	v_mov_b32_e32 v137, v128
	v_mov_b32_e32 v128, v133
	v_mov_b32_e32 v132, v134
	v_mov_b32_e32 v133, v130
	v_mov_b32_e32 v130, v135
	v_pk_add_f32 v[128:129], v[136:137], v[128:129]
	v_pk_add_f32 v[130:131], v[132:133], v[130:131]
	v_div_scale_f32 v142, s[0:1], v141, v141, 1.0
	v_pk_add_f32 v[128:129], v[128:129], v[130:131]
	v_rcp_f32_e32 v143, v142
	v_add_f32_e32 v128, v128, v129
	ds_bpermute_b32 v129, v171, v128
	v_div_fmas_f32 v130, v139, v151, v140
	v_div_fixup_f32 v131, v130, v149, 1.0
	v_fma_f32 v130, -v142, v143, 1.0
	v_fmac_f32_e32 v143, v130, v143
	s_waitcnt lgkmcnt(0)
	v_add_f32_e32 v128, v128, v129
	ds_bpermute_b32 v129, v185, v128
	v_div_scale_f32 v130, vcc, 1.0, v141, 1.0
	v_mul_f32_e32 v132, v130, v143
	v_fma_f32 v133, -v142, v132, v130
	s_waitcnt lgkmcnt(0)
	v_add_f32_e32 v128, v128, v129
	v_fmamk_f32 v128, v128, 0x3a000000, v179
	v_mul_f32_e32 v129, 0x4f800000, v128
	v_cmp_gt_f32_e64 s[0:1], s43, v128
	v_fmac_f32_e32 v132, v133, v143
	v_fma_f32 v130, -v142, v132, v130
	v_cndmask_b32_e64 v128, v128, v129, s[0:1]
	v_sqrt_f32_e32 v129, v128
	v_div_fmas_f32 v130, v130, v143, v132
	v_div_fixup_f32 v139, v130, v141, 1.0
	v_ashrrev_i32_e32 v171, 31, v170
	v_add_u32_e32 v133, -1, v129
	v_fma_f32 v134, -v133, v129, v128
	v_cmp_ge_f32_e64 s[6:7], 0, v134
	v_add_u32_e32 v134, 1, v129
	s_nop 0
	v_cndmask_b32_e64 v133, v129, v133, s[6:7]
	v_fma_f32 v129, -v134, v129, v128
	v_cmp_lt_f32_e64 s[6:7], 0, v129
	s_nop 1
	v_cndmask_b32_e64 v129, v133, v134, s[6:7]
	v_mul_f32_e32 v133, 0x37800000, v129
	v_cndmask_b32_e64 v129, v129, v133, s[0:1]
	v_cmp_class_f32_e64 s[0:1], v128, v180
	s_nop 1
	v_cndmask_b32_e64 v128, v129, v128, s[0:1]
	v_div_scale_f32 v129, s[0:1], v128, v128, 1.0
	v_rcp_f32_e32 v133, v129
	s_nop 0
	v_fma_f32 v130, -v129, v133, 1.0
	v_fmac_f32_e32 v133, v130, v133
	v_div_scale_f32 v130, vcc, 1.0, v128, 1.0
	v_mul_f32_e32 v132, v130, v133
	v_fma_f32 v134, -v129, v132, v130
	v_fmac_f32_e32 v132, v134, v133
	v_fma_f32 v129, -v129, v132, v130
	v_mul_f32_e32 v130, 0xbfb8aa3b, v160
	v_div_fmas_f32 v129, v129, v133, v132
	v_pk_mul_f32 v[136:137], v[124:125], v[130:131] op_sel_hi:[1,0]
	v_div_fixup_f32 v128, v129, v128, 1.0
	v_exp_f32_e32 v129, v136
	v_pk_mul_f32 v[134:135], v[126:127], v[130:131] op_sel_hi:[1,0]
	v_exp_f32_e32 v133, v137
	v_exp_f32_e32 v136, v134
	v_exp_f32_e32 v137, v135
	v_add_f32_e32 v129, 1.0, v129
	v_rcp_f32_e32 v134, v129
	v_add_f32_e32 v129, 1.0, v133
	v_rcp_f32_e32 v135, v129
	v_add_f32_e32 v129, 1.0, v136
	v_pk_mul_f32 v[126:127], v[116:117], v[130:131] op_sel_hi:[1,0]
	v_rcp_f32_e32 v136, v129
	v_add_f32_e32 v129, 1.0, v137
	v_pk_mul_f32 v[124:125], v[118:119], v[130:131] op_sel_hi:[1,0]
	v_exp_f32_e32 v126, v126
	v_exp_f32_e32 v127, v127
	v_rcp_f32_e32 v137, v129
	v_exp_f32_e32 v129, v124
	v_exp_f32_e32 v130, v125
	v_add_f32_e32 v124, 1.0, v126
	v_add_f32_e32 v125, 1.0, v127
	v_rcp_f32_e32 v124, v124
	v_rcp_f32_e32 v125, v125
	v_add_f32_e32 v126, 1.0, v129
	v_add_f32_e32 v127, 1.0, v130
	v_rcp_f32_e32 v126, v126
	v_rcp_f32_e32 v127, v127
	v_mul_f32_e32 v132, v160, v160
	v_pk_mul_f32 v[112:113], v[112:113], v[132:133] op_sel_hi:[1,0]
	v_pk_mul_f32 v[120:121], v[120:121], v[132:133] op_sel_hi:[1,0]
	v_pk_mul_f32 v[122:123], v[122:123], v[132:133] op_sel_hi:[1,0]
	v_pk_mul_f32 v[114:115], v[114:115], v[132:133] op_sel_hi:[1,0]
	v_pk_mul_f32 v[112:113], v[112:113], v[124:125]
	v_pk_mul_f32 v[122:123], v[122:123], v[136:137]
	v_pk_mul_f32 v[120:121], v[120:121], v[134:135]
	v_pk_mul_f32 v[114:115], v[114:115], v[126:127]
	v_cvt_pk_bf16_f32 v116, v120, v121
	v_cvt_pk_bf16_f32 v117, v122, v123
	v_cvt_pk_bf16_f32 v118, v112, v113
	v_mov_b64_e32 v[112:113], s[68:69]
	v_cvt_pk_bf16_f32 v119, v114, v115
	v_mad_i64_i32 v[120:121], s[0:1], v181, s44, v[112:113]
	v_lshlrev_b64 v[114:115], 1, v[170:171]
	v_lshl_add_u64 v[120:121], v[120:121], 0, v[114:115]
	global_store_dwordx4 v[120:121], v[116:119], off nt
	s_andn2_b64 vcc, exec, s[4:5]
	s_nop 0
	v_mul_f32_e32 v116, 0xbfb8aa3b, v188
	v_pk_mul_f32 v[122:123], v[108:109], v[116:117] op_sel_hi:[1,0]
	v_pk_mul_f32 v[120:121], v[110:111], v[116:117] op_sel_hi:[1,0]
	v_exp_f32_e32 v117, v122
	v_exp_f32_e32 v119, v123
	v_exp_f32_e32 v122, v120
	v_exp_f32_e32 v123, v121
	v_add_f32_e32 v117, 1.0, v117
	v_rcp_f32_e32 v120, v117
	v_add_f32_e32 v117, 1.0, v119
	v_rcp_f32_e32 v121, v117
	v_add_f32_e32 v117, 1.0, v122
	v_rcp_f32_e32 v122, v117
	v_add_f32_e32 v117, 1.0, v123
	v_pk_mul_f32 v[108:109], v[102:103], v[116:117] op_sel_hi:[1,0]
	v_pk_mul_f32 v[110:111], v[100:101], v[116:117] op_sel_hi:[1,0]
	v_rcp_f32_e32 v123, v117
	v_exp_f32_e32 v110, v110
	v_exp_f32_e32 v111, v111
	v_exp_f32_e32 v116, v108
	v_exp_f32_e32 v117, v109
	v_add_f32_e32 v108, 1.0, v110
	v_add_f32_e32 v109, 1.0, v111
	v_add_f32_e32 v110, 1.0, v116
	v_add_f32_e32 v111, 1.0, v117
	v_rcp_f32_e32 v108, v108
	v_rcp_f32_e32 v109, v109
	v_rcp_f32_e32 v110, v110
	v_rcp_f32_e32 v111, v111
	v_mul_f32_e32 v118, v188, v188
	v_pk_mul_f32 v[96:97], v[96:97], v[118:119] op_sel_hi:[1,0]
	v_pk_mul_f32 v[98:99], v[98:99], v[118:119] op_sel_hi:[1,0]
	v_pk_mul_f32 v[104:105], v[104:105], v[118:119] op_sel_hi:[1,0]
	v_pk_mul_f32 v[106:107], v[106:107], v[118:119] op_sel_hi:[1,0]
	v_pk_mul_f32 v[100:101], v[98:99], v[110:111]
	v_pk_mul_f32 v[98:99], v[96:97], v[108:109]
	v_add_u32_e32 v102, 16, v181
	v_pk_mul_f32 v[106:107], v[106:107], v[122:123]
	v_pk_mul_f32 v[104:105], v[104:105], v[120:121]
	s_nop 0
	v_cvt_pk_bf16_f32 v96, v104, v105
	v_cvt_pk_bf16_f32 v97, v106, v107
	v_cvt_pk_bf16_f32 v98, v98, v99
	v_cvt_pk_bf16_f32 v99, v100, v101
	v_mad_i64_i32 v[100:101], s[0:1], v102, s44, v[112:113]
	v_lshl_add_u64 v[100:101], v[100:101], 0, v[114:115]
	global_store_dwordx4 v[100:101], v[96:99], off nt
	s_nop 1
	v_mul_f32_e32 v96, 0xbfb8aa3b, v186
	v_pk_mul_f32 v[102:103], v[92:93], v[96:97] op_sel_hi:[1,0]
	v_pk_mul_f32 v[100:101], v[94:95], v[96:97] op_sel_hi:[1,0]
	v_exp_f32_e32 v97, v102
	v_exp_f32_e32 v99, v103
	v_exp_f32_e32 v102, v100
	v_exp_f32_e32 v103, v101
	v_add_f32_e32 v97, 1.0, v97
	v_rcp_f32_e32 v100, v97
	v_add_f32_e32 v97, 1.0, v99
	v_rcp_f32_e32 v101, v97
	v_add_f32_e32 v97, 1.0, v102
	v_rcp_f32_e32 v102, v97
	v_add_f32_e32 v97, 1.0, v103
	v_pk_mul_f32 v[92:93], v[86:87], v[96:97] op_sel_hi:[1,0]
	v_pk_mul_f32 v[94:95], v[84:85], v[96:97] op_sel_hi:[1,0]
	v_rcp_f32_e32 v103, v97
	v_exp_f32_e32 v94, v94
	v_exp_f32_e32 v95, v95
	v_exp_f32_e32 v96, v92
	v_exp_f32_e32 v97, v93
	v_add_f32_e32 v92, 1.0, v94
	v_add_f32_e32 v93, 1.0, v95
	v_add_f32_e32 v94, 1.0, v96
	v_add_f32_e32 v95, 1.0, v97
	v_rcp_f32_e32 v92, v92
	v_rcp_f32_e32 v93, v93
	v_rcp_f32_e32 v94, v94
	v_rcp_f32_e32 v95, v95
	v_mul_f32_e32 v98, v186, v186
	v_pk_mul_f32 v[80:81], v[80:81], v[98:99] op_sel_hi:[1,0]
	v_pk_mul_f32 v[82:83], v[82:83], v[98:99] op_sel_hi:[1,0]
	v_pk_mul_f32 v[88:89], v[88:89], v[98:99] op_sel_hi:[1,0]
	v_pk_mul_f32 v[90:91], v[90:91], v[98:99] op_sel_hi:[1,0]
	v_pk_mul_f32 v[84:85], v[82:83], v[94:95]
	v_pk_mul_f32 v[82:83], v[80:81], v[92:93]
	v_add_u32_e32 v86, 32, v181
	v_pk_mul_f32 v[90:91], v[90:91], v[102:103]
	v_pk_mul_f32 v[88:89], v[88:89], v[100:101]
	s_nop 0
	v_cvt_pk_bf16_f32 v80, v88, v89
	v_cvt_pk_bf16_f32 v81, v90, v91
	v_cvt_pk_bf16_f32 v82, v82, v83
	v_cvt_pk_bf16_f32 v83, v84, v85
	v_mad_i64_i32 v[84:85], s[0:1], v86, s44, v[112:113]
	v_lshl_add_u64 v[84:85], v[84:85], 0, v[114:115]
	global_store_dwordx4 v[84:85], v[80:83], off nt
	s_nop 1
	v_mul_f32_e32 v80, 0xbfb8aa3b, v146
	v_pk_mul_f32 v[86:87], v[76:77], v[80:81] op_sel_hi:[1,0]
	v_pk_mul_f32 v[84:85], v[78:79], v[80:81] op_sel_hi:[1,0]
	v_exp_f32_e32 v81, v86
	v_exp_f32_e32 v83, v87
	v_exp_f32_e32 v86, v84
	v_exp_f32_e32 v87, v85
	v_add_f32_e32 v81, 1.0, v81
	v_rcp_f32_e32 v84, v81
	v_add_f32_e32 v81, 1.0, v83
	v_rcp_f32_e32 v85, v81
	v_add_f32_e32 v81, 1.0, v86
	v_rcp_f32_e32 v86, v81
	v_add_f32_e32 v81, 1.0, v87
	v_pk_mul_f32 v[76:77], v[70:71], v[80:81] op_sel_hi:[1,0]
	v_pk_mul_f32 v[78:79], v[68:69], v[80:81] op_sel_hi:[1,0]
	v_rcp_f32_e32 v87, v81
	v_exp_f32_e32 v78, v78
	v_exp_f32_e32 v79, v79
	v_exp_f32_e32 v80, v76
	v_exp_f32_e32 v81, v77
	v_add_f32_e32 v76, 1.0, v78
	v_add_f32_e32 v77, 1.0, v79
	v_add_f32_e32 v78, 1.0, v80
	v_add_f32_e32 v79, 1.0, v81
	v_rcp_f32_e32 v76, v76
	v_rcp_f32_e32 v77, v77
	v_rcp_f32_e32 v78, v78
	v_rcp_f32_e32 v79, v79
	v_mul_f32_e32 v82, v146, v146
	v_pk_mul_f32 v[64:65], v[64:65], v[82:83] op_sel_hi:[1,0]
	v_pk_mul_f32 v[66:67], v[66:67], v[82:83] op_sel_hi:[1,0]
	v_pk_mul_f32 v[72:73], v[72:73], v[82:83] op_sel_hi:[1,0]
	v_pk_mul_f32 v[74:75], v[74:75], v[82:83] op_sel_hi:[1,0]
	v_pk_mul_f32 v[68:69], v[66:67], v[78:79]
	v_pk_mul_f32 v[66:67], v[64:65], v[76:77]
	v_add_u32_e32 v70, 48, v181
	v_pk_mul_f32 v[74:75], v[74:75], v[86:87]
	v_pk_mul_f32 v[72:73], v[72:73], v[84:85]
	s_nop 0
	v_cvt_pk_bf16_f32 v64, v72, v73
	v_cvt_pk_bf16_f32 v65, v74, v75
	v_cvt_pk_bf16_f32 v66, v66, v67
	v_cvt_pk_bf16_f32 v67, v68, v69
	v_mad_i64_i32 v[68:69], s[0:1], v70, s44, v[112:113]
	v_lshl_add_u64 v[68:69], v[68:69], 0, v[114:115]
	global_store_dwordx4 v[68:69], v[64:67], off nt
	s_nop 1
	v_add_u32_e32 v65, 0x80, v181
	v_mul_f32_e32 v64, 0xbfb8aa3b, v138
	v_pk_mul_f32 v[70:71], v[60:61], v[64:65] op_sel_hi:[1,0]
	v_pk_mul_f32 v[68:69], v[62:63], v[64:65] op_sel_hi:[1,0]
	v_exp_f32_e32 v67, v70
	v_exp_f32_e32 v70, v71
	v_exp_f32_e32 v71, v68
	v_exp_f32_e32 v72, v69
	v_add_f32_e32 v67, 1.0, v67
	v_rcp_f32_e32 v68, v67
	v_add_f32_e32 v67, 1.0, v70
	v_rcp_f32_e32 v69, v67
	v_add_f32_e32 v67, 1.0, v71
	v_mul_f32_e32 v66, v138, v138
	v_rcp_f32_e32 v70, v67
	v_add_f32_e32 v67, 1.0, v72
	v_pk_mul_f32 v[60:61], v[54:55], v[64:65] op_sel_hi:[1,0]
	v_pk_mul_f32 v[62:63], v[52:53], v[64:65] op_sel_hi:[1,0]
	v_rcp_f32_e32 v71, v67
	v_pk_mul_f32 v[56:57], v[56:57], v[66:67] op_sel_hi:[1,0]
	v_pk_mul_f32 v[58:59], v[58:59], v[66:67] op_sel_hi:[1,0]
	v_exp_f32_e32 v62, v62
	v_exp_f32_e32 v63, v63
	v_exp_f32_e32 v64, v60
	v_exp_f32_e32 v67, v61
	v_add_f32_e32 v60, 1.0, v62
	v_add_f32_e32 v61, 1.0, v63
	v_add_f32_e32 v62, 1.0, v64
	v_add_f32_e32 v63, 1.0, v67
	v_rcp_f32_e32 v60, v60
	v_rcp_f32_e32 v61, v61
	v_rcp_f32_e32 v62, v62
	v_rcp_f32_e32 v63, v63
	v_pk_mul_f32 v[48:49], v[48:49], v[66:67] op_sel_hi:[1,0]
	v_pk_mul_f32 v[50:51], v[50:51], v[66:67] op_sel_hi:[1,0]
	v_pk_mul_f32 v[58:59], v[58:59], v[70:71]
	v_pk_mul_f32 v[52:53], v[50:51], v[62:63]
	v_pk_mul_f32 v[50:51], v[48:49], v[60:61]
	v_pk_mul_f32 v[56:57], v[56:57], v[68:69]
	s_nop 0
	v_cvt_pk_bf16_f32 v48, v56, v57
	v_cvt_pk_bf16_f32 v49, v58, v59
	v_cvt_pk_bf16_f32 v50, v50, v51
	v_cvt_pk_bf16_f32 v51, v52, v53
	v_mad_i64_i32 v[52:53], s[0:1], v65, s44, v[112:113]
	v_lshl_add_u64 v[52:53], v[52:53], 0, v[114:115]
	global_store_dwordx4 v[52:53], v[48:51], off nt
	s_nop 1
	v_mul_f32_e32 v48, 0xbfb8aa3b, v131
	v_pk_mul_f32 v[54:55], v[44:45], v[48:49] op_sel_hi:[1,0]
	v_pk_mul_f32 v[52:53], v[46:47], v[48:49] op_sel_hi:[1,0]
	v_exp_f32_e32 v49, v54
	v_exp_f32_e32 v51, v55
	v_exp_f32_e32 v54, v52
	v_exp_f32_e32 v55, v53
	v_add_f32_e32 v49, 1.0, v49
	v_rcp_f32_e32 v52, v49
	v_add_f32_e32 v49, 1.0, v51
	v_rcp_f32_e32 v53, v49
	v_add_f32_e32 v49, 1.0, v54
	v_rcp_f32_e32 v54, v49
	v_add_f32_e32 v49, 1.0, v55
	v_pk_mul_f32 v[44:45], v[38:39], v[48:49] op_sel_hi:[1,0]
	v_pk_mul_f32 v[46:47], v[36:37], v[48:49] op_sel_hi:[1,0]
	v_rcp_f32_e32 v55, v49
	v_exp_f32_e32 v46, v46
	v_exp_f32_e32 v47, v47
	v_exp_f32_e32 v48, v44
	v_exp_f32_e32 v49, v45
	v_add_f32_e32 v44, 1.0, v46
	v_add_f32_e32 v45, 1.0, v47
	v_add_f32_e32 v46, 1.0, v48
	v_add_f32_e32 v47, 1.0, v49
	v_rcp_f32_e32 v44, v44
	v_rcp_f32_e32 v45, v45
	v_rcp_f32_e32 v46, v46
	v_rcp_f32_e32 v47, v47
	v_mul_f32_e32 v50, v131, v131
	v_pk_mul_f32 v[32:33], v[32:33], v[50:51] op_sel_hi:[1,0]
	v_pk_mul_f32 v[34:35], v[34:35], v[50:51] op_sel_hi:[1,0]
	v_pk_mul_f32 v[40:41], v[40:41], v[50:51] op_sel_hi:[1,0]
	v_pk_mul_f32 v[42:43], v[42:43], v[50:51] op_sel_hi:[1,0]
	v_pk_mul_f32 v[36:37], v[34:35], v[46:47]
	v_pk_mul_f32 v[34:35], v[32:33], v[44:45]
	v_add_u32_e32 v38, 0x90, v181
	v_pk_mul_f32 v[42:43], v[42:43], v[54:55]
	v_pk_mul_f32 v[40:41], v[40:41], v[52:53]
	s_nop 0
	v_cvt_pk_bf16_f32 v32, v40, v41
	v_cvt_pk_bf16_f32 v33, v42, v43
	v_cvt_pk_bf16_f32 v34, v34, v35
	v_cvt_pk_bf16_f32 v35, v36, v37
	v_mad_i64_i32 v[36:37], s[0:1], v38, s44, v[112:113]
	v_lshl_add_u64 v[36:37], v[36:37], 0, v[114:115]
	global_store_dwordx4 v[36:37], v[32:35], off nt
	s_nop 1
	v_mul_f32_e32 v32, 0xbfb8aa3b, v139
	v_pk_mul_f32 v[38:39], v[28:29], v[32:33] op_sel_hi:[1,0]
	v_pk_mul_f32 v[36:37], v[30:31], v[32:33] op_sel_hi:[1,0]
	v_exp_f32_e32 v33, v38
	v_exp_f32_e32 v35, v39
	v_exp_f32_e32 v38, v36
	v_exp_f32_e32 v39, v37
	v_add_f32_e32 v33, 1.0, v33
	v_rcp_f32_e32 v36, v33
	v_add_f32_e32 v33, 1.0, v35
	v_rcp_f32_e32 v37, v33
	v_add_f32_e32 v33, 1.0, v38
	v_rcp_f32_e32 v38, v33
	v_add_f32_e32 v33, 1.0, v39
	v_pk_mul_f32 v[28:29], v[22:23], v[32:33] op_sel_hi:[1,0]
	v_pk_mul_f32 v[30:31], v[20:21], v[32:33] op_sel_hi:[1,0]
	v_rcp_f32_e32 v39, v33
	v_exp_f32_e32 v30, v30
	v_exp_f32_e32 v31, v31
	v_exp_f32_e32 v32, v28
	v_exp_f32_e32 v33, v29
	v_add_f32_e32 v28, 1.0, v30
	v_add_f32_e32 v29, 1.0, v31
	v_add_f32_e32 v30, 1.0, v32
	v_add_f32_e32 v31, 1.0, v33
	v_rcp_f32_e32 v28, v28
	v_rcp_f32_e32 v29, v29
	v_rcp_f32_e32 v30, v30
	v_rcp_f32_e32 v31, v31
	v_mul_f32_e32 v34, v139, v139
	v_pk_mul_f32 v[16:17], v[16:17], v[34:35] op_sel_hi:[1,0]
	v_pk_mul_f32 v[18:19], v[18:19], v[34:35] op_sel_hi:[1,0]
	v_pk_mul_f32 v[24:25], v[24:25], v[34:35] op_sel_hi:[1,0]
	v_pk_mul_f32 v[26:27], v[26:27], v[34:35] op_sel_hi:[1,0]
	v_pk_mul_f32 v[20:21], v[18:19], v[30:31]
	v_pk_mul_f32 v[18:19], v[16:17], v[28:29]
	v_add_u32_e32 v22, 0xa0, v181
	v_pk_mul_f32 v[26:27], v[26:27], v[38:39]
	v_pk_mul_f32 v[24:25], v[24:25], v[36:37]
	s_nop 0
	v_cvt_pk_bf16_f32 v16, v24, v25
	v_cvt_pk_bf16_f32 v17, v26, v27
	v_cvt_pk_bf16_f32 v18, v18, v19
	v_cvt_pk_bf16_f32 v19, v20, v21
	v_mad_i64_i32 v[20:21], s[0:1], v22, s44, v[112:113]
	v_lshl_add_u64 v[20:21], v[20:21], 0, v[114:115]
	global_store_dwordx4 v[20:21], v[16:19], off nt
	s_nop 1
	v_mul_f32_e32 v16, 0xbfb8aa3b, v128
	v_pk_mul_f32 v[22:23], v[12:13], v[16:17] op_sel_hi:[1,0]
	v_pk_mul_f32 v[20:21], v[14:15], v[16:17] op_sel_hi:[1,0]
	v_exp_f32_e32 v17, v22
	v_exp_f32_e32 v19, v23
	v_exp_f32_e32 v22, v20
	v_exp_f32_e32 v23, v21
	v_add_f32_e32 v17, 1.0, v17
	v_rcp_f32_e32 v20, v17
	v_add_f32_e32 v17, 1.0, v19
	v_rcp_f32_e32 v21, v17
	v_add_f32_e32 v17, 1.0, v22
	v_rcp_f32_e32 v22, v17
	v_add_f32_e32 v17, 1.0, v23
	v_pk_mul_f32 v[12:13], v[6:7], v[16:17] op_sel_hi:[1,0]
	v_pk_mul_f32 v[14:15], v[4:5], v[16:17] op_sel_hi:[1,0]
	v_rcp_f32_e32 v23, v17
	v_exp_f32_e32 v14, v14
	v_exp_f32_e32 v15, v15
	v_exp_f32_e32 v16, v12
	v_exp_f32_e32 v17, v13
	v_add_f32_e32 v12, 1.0, v14
	v_add_f32_e32 v13, 1.0, v15
	v_add_f32_e32 v14, 1.0, v16
	v_add_f32_e32 v15, 1.0, v17
	v_rcp_f32_e32 v12, v12
	v_rcp_f32_e32 v13, v13
	v_rcp_f32_e32 v14, v14
	v_rcp_f32_e32 v15, v15
	v_mul_f32_e32 v18, v128, v128
	v_pk_mul_f32 v[0:1], v[0:1], v[18:19] op_sel_hi:[1,0]
	v_pk_mul_f32 v[2:3], v[2:3], v[18:19] op_sel_hi:[1,0]
	v_pk_mul_f32 v[8:9], v[8:9], v[18:19] op_sel_hi:[1,0]
	v_pk_mul_f32 v[10:11], v[10:11], v[18:19] op_sel_hi:[1,0]
	v_pk_mul_f32 v[4:5], v[2:3], v[14:15]
	v_pk_mul_f32 v[2:3], v[0:1], v[12:13]
	v_add_u32_e32 v6, 0xb0, v181
	v_pk_mul_f32 v[10:11], v[10:11], v[22:23]
	v_pk_mul_f32 v[8:9], v[8:9], v[20:21]
	s_nop 0
	v_cvt_pk_bf16_f32 v0, v8, v9
	v_cvt_pk_bf16_f32 v1, v10, v11
	v_cvt_pk_bf16_f32 v2, v2, v3
	v_cvt_pk_bf16_f32 v3, v4, v5
	v_mad_i64_i32 v[4:5], s[0:1], v6, s44, v[112:113]
	v_lshl_add_u64 v[4:5], v[4:5], 0, v[114:115]
	s_mov_b64 s[0:1], -1
	global_store_dwordx4 v[4:5], v[0:3], off nt
	s_cbranch_vccnz .LBB0_1360
	s_andn2_b64 vcc, exec, s[8:9]
	s_cbranch_vccnz .LBB0_1359
	s_barrier
	s_branch .LBB0_1359
